# GU1 epilogue row-scale loads prefetched at tile start (no vmcnt drain), and blocks with 16 GU tiles delayed half a tile so output store bursts desynchronise
# baseline (speedup 1.0000x reference)
; #define PG8_BAR __builtin_amdgcn_s_barrier()
;     __device__ bool next(int i, Unit& u) const {
;         const long L = (long)i * G + c; if (L >= nwg) return false;
;         int wgid = (int)L; { const int q = nwg / NXCD, r = nwg % NXCD, xcd = wgid % NXCD, off = wgid / NXCD; wgid = (xcd < r ? xcd * (q + 1) : r * (q + 1) + (xcd - r) * q) + off; }
;         const int nig = WGM * nN, gid = wgid / nig, fm = gid * WGM, gsz = (nM - fm) < WGM ? (nM - fm) : WGM;
; template <class Epi>
; __device__ __forceinline__ void gemm_phase(LAS unsigned char* lds, const Gemm g, const StaticOrder& S, const Epi& E) {
;     ...
;     const int tid = tid_, wid = __builtin_amdgcn_readfirstlane(tid >> 6), lane = tid & 63, wr = wid >> 2, wc = wid & 3, fr = lane & 15, fq = lane >> 4;
;     const int K = g.K, nt = K / BK, lda = g.lda;
;     unsigned voffA[2], voffB[2];
; #pragma unroll
;     for (int i = 0; i < 2; ++i) { int R, C; stage_rc(tid * 16 + i * 8192, R, C); const int Rb = (R & ~31) + perm32(R & 31);
;         voffA[i] = (unsigned)(R * lda + C) * 2u; voffB[i] = (unsigned)(Rb * K + C) * 2u; }
;     const unsigned kstep = (unsigned)(BK * 2);
;     const unsigned hstepA = (unsigned)(HALF * lda * 2), hstepB = (unsigned)(HALF * K * 2);
;     const size_t tstepA = 2 * (size_t)hstepA, tstepB = 2 * (size_t)hstepB;
;     const unsigned ldsw = (unsigned)wid * 1024u;
;     const int aoff = lds_byte(wr * 64 + fr, fq * 8), boff = lds_byte(wc * 32 + fr, fq * 8);
;     ...
;     Unit cur, nxt; int ui = 0;
;     if (!S.next(0, cur)) return;
;     f32x4 acc[2][2][4][2];
; #pragma unroll
;     for (int a = 0; a < 2; ++a)
; #pragma unroll
;         for (int b = 0; b < 2; ++b)
; #pragma unroll
;             for (int m = 0; m < 4; ++m)
; #pragma unroll
;                 for (int n = 0; n < 2; ++n) acc[a][b][m][n] = (f32x4){0.f, 0.f, 0.f, 0.f};
;     bf16x8 At[4][2], B0[2][2], B1[2][2];
;     const char* cA = (const char*)g.A + (size_t)cur.pm * tstepA; const char* cB = (const char*)g.Bt + (size_t)cur.pn * tstepB;
;     PG8_STAGE(PG8_SB(0, 0), cB, voffB); PG8_STAGE(PG8_SB(0, 1), cB + hstepB, voffB); PG8_STAGE(PG8_SA(0, 0), cA, voffA); PG8_STAGE(PG8_SA(0, 1), cA + hstepA, voffA);
;     if (wr == 1) PG8_BAR;
;     PG8_WAIT_V(2); PG8_BAR;
;     PG8_STAGE(PG8_SB(1, 0), cB + kstep, voffB); PG8_STAGE(PG8_SA(1, 0), cA + kstep, voffA); PG8_STAGE(PG8_SB(1, 1), cB + hstepB + kstep, voffB);
;     PG8_WAIT_V(6); PG8_BAR;
.LBB0_153:
	s_or_b64 exec, exec, s[34:35]
	v_readlane_b32 s16, v234, 16
	s_mov_b64 s[42:43], s[72:73]
	v_readlane_b32 s30, v234, 30
	v_readlane_b32 s31, v234, 31
	s_waitcnt lgkmcnt(0)
	s_barrier
	s_cselect_b32 s92, 1, 0
	s_cmp_lt_u32 s14, 128
	s_cbranch_scc1 .Lstg_3
	s_sleep 127
	s_sleep 127
	s_sleep 127
	s_sleep 127
	s_sleep 127
.Lstg_3:
	s_cmp_lg_u32 s92, 0
	v_readlane_b32 s17, v234, 17
	v_readlane_b32 s18, v234, 18
	v_readlane_b32 s19, v234, 19
	v_readlane_b32 s20, v234, 20
	v_readlane_b32 s21, v234, 21
	v_readlane_b32 s22, v234, 22
	v_readlane_b32 s23, v234, 23
	v_readlane_b32 s24, v234, 24
	v_readlane_b32 s25, v234, 25
	v_readlane_b32 s26, v234, 26
	v_readlane_b32 s27, v234, 27
	v_readlane_b32 s28, v234, 28
	v_readlane_b32 s29, v234, 29
	s_mov_b64 s[2:3], s[42:43]
	v_writelane_b32 v234, s16, 16
	v_mov_b32_e32 v8, v154
	s_cmpk_lt_i32 s14, 0x1080
	v_writelane_b32 v234, s17, 17
	v_writelane_b32 v234, s18, 18
	v_writelane_b32 v234, s19, 19
	v_writelane_b32 v234, s20, 20
	v_writelane_b32 v234, s21, 21
	v_writelane_b32 v234, s22, 22
	v_writelane_b32 v234, s23, 23
	v_writelane_b32 v234, s24, 24
	v_writelane_b32 v234, s25, 25
	v_writelane_b32 v234, s26, 26
	v_writelane_b32 v234, s27, 27
	v_writelane_b32 v234, s28, 28
	v_writelane_b32 v234, s29, 29
	v_writelane_b32 v234, s30, 30
	s_cselect_b64 s[38:39], -1, 0
	s_cmpk_gt_i32 s14, 0x107f
	v_readfirstlane_b32 s1, v8
	v_writelane_b32 v234, s31, 31
	s_cbranch_scc1 .LBB0_169
	v_lshlrev_b32_e32 v0, 4, v8
	v_add_u32_e32 v1, 0x2000, v0
	v_ashrrev_i32_e32 v2, 31, v1
	v_lshrrev_b32_e32 v2, 22, v2
	v_add_u32_e32 v2, v1, v2
	v_ashrrev_i32_e32 v9, 10, v2
	v_mul_i32_i24_e32 v2, 0x400, v9
	v_sub_u32_e32 v1, v1, v2
	v_lshrrev_b32_e32 v2, 4, v1
	v_bitop3_b32 v1, v2, v1, 32 bitop3:0x6c
	v_ashrrev_i32_e32 v2, 31, v1
	v_lshrrev_b32_e32 v2, 26, v2
	v_add_u32_e32 v2, v1, v2
	v_lshlrev_b32_e32 v3, 3, v9
	v_ashrrev_i32_e32 v10, 6, v2
	v_and_b32_e32 v3, -16, v3
	v_add_u32_e32 v3, v10, v3
	v_and_b32_e32 v4, 3, v10
	s_mov_b32 s0, 0x1fffe0
	v_lshrrev_b32_e32 v5, 2, v3
	v_lshlrev_b32_e32 v6, 1, v3
	v_and_b32_e32 v2, 0xc0, v2
	v_and_or_b32 v4, v3, s0, v4
	v_and_b32_e32 v5, 4, v5
	v_and_b32_e32 v6, 24, v6
	v_sub_u32_e32 v1, v1, v2
	v_mov_b32_e32 v2, 1
	v_or3_b32 v4, v4, v5, v6
	v_lshlrev_b32_e32 v5, 5, v9
	v_ashrrev_i16_sdwa v1, v2, sext(v1) dst_sel:DWORD dst_unused:UNUSED_PAD src0_sel:DWORD src1_sel:BYTE_0
	v_and_b32_e32 v5, 32, v5
	v_bfe_i32 v11, v1, 0, 16
	v_add_lshl_u32 v1, v5, v11, 1
	v_lshl_add_u32 v128, v4, 11, v1
	v_lshl_add_u32 v130, v3, 11, v1
	v_bfe_i32 v1, v8, 27, 1
	v_lshrrev_b32_e32 v1, 22, v1
	v_add_u32_e32 v1, v0, v1
	v_and_b32_e32 v1, 0xfffffc00, v1
	v_sub_u32_e32 v0, v0, v1
	v_lshrrev_b32_e32 v1, 4, v0
	v_ashrrev_i32_e32 v3, 31, v8
	v_bitop3_b32 v0, v1, v0, 32 bitop3:0x6c
	v_lshrrev_b32_e32 v3, 26, v3
	v_ashrrev_i32_e32 v1, 31, v0
	v_add_u32_e32 v3, v8, v3
	s_add_u32 s30, s2, 0x200000
	v_lshrrev_b32_e32 v1, 26, v1
	v_ashrrev_i32_e32 v13, 6, v3
	s_addc_u32 s31, s3, 0
	v_add_u32_e32 v1, v0, v1
	v_lshlrev_b32_e32 v3, 3, v13
	s_add_u32 s33, s2, 0x5400000
	v_ashrrev_i32_e32 v12, 6, v1
	v_and_b32_e32 v3, -16, v3
	s_addc_u32 s34, s3, 0
	v_add_u32_e32 v3, v12, v3
	v_and_b32_e32 v4, 3, v12
	s_ashr_i32 s36, s14, 31
	v_and_or_b32 v4, v3, s0, v4
	s_lshr_b32 s0, s36, 29
	s_add_i32 s0, s14, s0
	s_ashr_i32 s8, s1, 6
	s_ashr_i32 s4, s0, 3
	s_and_b32 s0, s0, -8
	s_ashr_i32 s10, s1, 8
	s_lshl_b32 s35, s8, 10
	s_sub_i32 s0, s14, s0
	s_cmp_lt_i32 s0, 0
	s_movk_i32 s37, 0x211
	s_cselect_b32 s5, s37, 0x210
	s_mul_i32 s0, s0, s5
	s_add_i32 s0, s0, s4
	s_mul_hi_i32 s4, s0, 0x2e8ba2e9
	s_lshr_b32 s5, s4, 31
	s_ashr_i32 s4, s4, 5
	s_add_i32 s4, s4, s5
	s_lshl_b32 s5, s4, 3
	s_mulk_i32 s4, 0xb0
	s_sub_i32 s4, s0, s4
	s_sext_i32_i16 s0, s4
	s_bfe_u32 s0, s0, 0x3001c
	s_add_i32 s6, s4, s0
	s_sext_i32_i16 s0, s6
	s_and_b32 s6, s6, 0xfff8
	s_sub_i32 s4, s4, s6
	s_sext_i32_i16 s4, s4
	v_lshrrev_b32_e32 v5, 2, v3
	v_lshlrev_b32_e32 v6, 1, v3
	v_and_b32_e32 v1, 0xc0, v1
	s_lshr_b32 s0, s0, 3
	s_add_i32 s22, s5, s4
	v_and_b32_e32 v5, 4, v5
	v_and_b32_e32 v6, 24, v6
	v_sub_u32_e32 v0, v0, v1
	s_ashr_i32 s23, s22, 31
	s_bfe_i64 s[6:7], s[0:1], 0x100000
	v_or3_b32 v4, v4, v5, v6
	v_lshlrev_b32_e32 v5, 5, v13
	v_ashrrev_i16_sdwa v0, v2, sext(v0) dst_sel:DWORD dst_unused:UNUSED_PAD src0_sel:DWORD src1_sel:BYTE_0
	s_lshl_b64 s[4:5], s[22:23], 19
	s_lshl_b64 s[6:7], s[6:7], 19
	v_and_b32_e32 v5, 32, v5
	v_bfe_i32 v14, v0, 0, 16
	s_add_u32 s24, s30, s6
	v_add_lshl_u32 v0, v5, v14, 1
	s_addc_u32 s25, s31, s7
	s_add_i32 s23, s35, 0
	v_lshl_add_u32 v132, v4, 11, v0
	s_add_i32 m0, s23, 0x10000
	v_lshl_add_u32 v134, v3, 11, v0
	global_load_lds_dwordx4 v132, s[24:25]
	s_add_i32 m0, s23, 0x12000
	s_add_u32 s6, s24, 0x40000
	global_load_lds_dwordx4 v128, s[24:25]
	s_addc_u32 s7, s25, 0
	s_add_i32 m0, s23, 0x14000
	v_mov_b32_e32 v133, 0
	global_load_lds_dwordx4 v132, s[6:7]
	s_add_i32 m0, s23, 0x16000
	s_add_u32 s26, s33, s4
	s_addc_u32 s27, s34, s5
	s_add_i32 s44, s23, 0x2000
	global_load_lds_dwordx4 v128, s[6:7]
	s_mov_b32 m0, s23
	s_add_u32 s4, s26, 0x40000
	global_load_lds_dwordx4 v134, s[26:27]
	s_mov_b32 m0, s44
	s_addc_u32 s5, s27, 0
	s_add_i32 s45, s23, 0x4000
	global_load_lds_dwordx4 v130, s[26:27]
	s_mov_b32 m0, s45
	s_add_i32 s46, s23, 0x6000
	global_load_lds_dwordx4 v134, s[4:5]
	s_mov_b32 m0, s46
	v_mov_b32_e32 v129, v133
	global_load_lds_dwordx4 v130, s[4:5]
	v_mov_b32_e32 v135, v133
	v_mov_b32_e32 v131, v133
	s_cmp_eq_u32 s10, 1
	s_mov_b32 s47, 0
	v_lshl_add_u64 v[6:7], s[24:25], 0, v[132:133]
	v_lshl_add_u64 v[4:5], s[24:25], 0, v[128:129]
	v_lshl_add_u64 v[0:1], s[26:27], 0, v[134:135]
	s_cselect_b64 s[4:5], -1, 0
	s_cmp_lg_u32 s10, 1
	v_lshl_add_u64 v[2:3], s[26:27], 0, v[130:131]
	s_cbranch_scc1 .LBB0_156
	s_barrier

;     __device__ bool next(int i, Unit& u) const {
;         const long L = (long)i * G + c; if (L >= nwg) return false;
;         int wgid = (int)L; { const int q = nwg / NXCD, r = nwg % NXCD, xcd = wgid % NXCD, off = wgid / NXCD; wgid = (xcd < r ? xcd * (q + 1) : r * (q + 1) + (xcd - r) * q) + off; }
;         const int nig = WGM * nN, gid = wgid / nig, fm = gid * WGM, gsz = (nM - fm) < WGM ? (nM - fm) : WGM;
;         u.pm = fm + ((wgid % nig) % gsz); u.pn = (wgid % nig) / gsz; return true;
;     }
;     __device__ __forceinline__ void operator()(const f32x4 (&acc)[2][2][4][2], const Unit& u, int wr, int wc, int fr, int fq) const {
;     ...
;         for (int i = 0; i < 8; ++i) rsv[i] = (NP == 16) ? row_ss16_coop(ss, row0 + (i >> 2) * HALF + (i & 3) * 16, fq) : row_ss<1>(ss, row0 + (i >> 2) * HALF + (i & 3) * 16);
; #pragma unroll
;         for (int i = 0; i < 8; ++i) rsv[i] = __builtin_amdgcn_rsqf(rsv[i] * (1.0f / 1024.0f) + EPS);
.LBB0_159:
	v_lshl_add_u32 v244, s22, 8, v146
	v_ashrrev_i32_e32 v245, 31, v244
	v_lshl_add_u64 v[246:247], v[244:245], 2, s[2:3]
	global_load_dword v235, v[246:247], off
	global_load_dword v236, v[246:247], off offset:64
	global_load_dword v237, v[246:247], off offset:128
	global_load_dword v238, v[246:247], off offset:192
	global_load_dword v239, v[246:247], off offset:512
	global_load_dword v240, v[246:247], off offset:576
	global_load_dword v241, v[246:247], off offset:640
	global_load_dword v242, v[246:247], off offset:704
	s_add_i32 s47, s47, 1
	s_mul_i32 s0, s47, s52
	s_mul_hi_u32 s1, s47, s53
	s_add_i32 s1, s1, s0
	s_mul_i32 s0, s47, s53
	s_add_u32 s18, s0, s14
	s_addc_u32 s19, s1, s36
	v_cmp_gt_i64_e32 vcc, s[18:19], v[142:143]
	v_cmp_lt_i64_e64 s[0:1], s[18:19], v[140:141]
	s_cbranch_vccnz .LBB0_161
	s_ashr_i32 s12, s18, 31
	s_lshr_b32 s12, s12, 29
	s_add_i32 s12, s18, s12
	s_ashr_i32 s13, s12, 3
	s_and_b32 s12, s12, -8
	s_sub_i32 s12, s18, s12
	s_cmp_lt_i32 s12, 0
	s_cselect_b32 s16, s37, 0x210
	s_mul_i32 s12, s12, s16
	s_add_i32 s12, s12, s13
	s_mul_hi_i32 s13, s12, 0x2e8ba2e9
	s_lshr_b32 s16, s13, 31
	s_ashr_i32 s13, s13, 5
	s_add_i32 s13, s13, s16
	s_lshl_b32 s16, s13, 3
	s_sub_i32 s17, 0xc0, s16
	s_min_i32 s17, s17, 8
	s_abs_i32 s18, s17
	v_cvt_f32_u32_e32 v0, s18
	s_sub_i32 s20, 0, s18
	s_mulk_i32 s13, 0xb0
	s_sub_i32 s13, s12, s13
	v_rcp_iflag_f32_e32 v0, v0
	s_abs_i32 s12, s13
	s_xor_b32 s19, s13, s17
	s_ashr_i32 s19, s19, 31
	v_mul_f32_e32 v0, 0x4f7ffffe, v0
	v_cvt_u32_f32_e32 v0, v0
	s_nop 0
	v_readfirstlane_b32 s21, v0
	s_mul_i32 s20, s20, s21
	s_mul_hi_u32 s20, s21, s20
	s_add_i32 s21, s21, s20
	s_mul_hi_u32 s20, s12, s21
	s_mul_i32 s21, s20, s18
	s_sub_i32 s12, s12, s21
	s_add_i32 s28, s20, 1
	s_sub_i32 s21, s12, s18
	s_cmp_ge_u32 s12, s18
	s_cselect_b32 s20, s28, s20
	s_cselect_b32 s12, s21, s12
	s_add_i32 s21, s20, 1
	s_cmp_ge_u32 s12, s18
	s_cselect_b32 s12, s21, s20
	s_xor_b32 s12, s12, s19
	s_sub_i32 s12, s12, s19
	s_mul_i32 s17, s12, s17
	s_sub_i32 s13, s13, s17
	s_add_i32 s16, s16, s13

; #define GAS __attribute__((address_space(1)))
; __device__ __forceinline__ unsigned cvt_pk_bf16(float lo, float hi) { f32x2_t v = {lo, hi}; bf16x2_t b = __builtin_convertvector(v, bf16x2_t); return __builtin_bit_cast(unsigned, b); }
;     __device__ __forceinline__ void operator()(const f32x4 (&acc)[2][2][4][2], const Unit& u, int wr, int wc, int fr, int fq) const {
;         const int row0 = u.pm * BM + wr * 64 + fr, col0 = u.pn * 128 + wc * 32 + 8 * fq;
;         float rsv[8];
; #pragma unroll
;         for (int i = 0; i < 8; ++i) rsv[i] = (NP == 16) ? row_ss16_coop(ss, row0 + (i >> 2) * HALF + (i & 3) * 16, fq) : row_ss<1>(ss, row0 + (i >> 2) * HALF + (i & 3) * 16);
; #pragma unroll
;         for (int i = 0; i < 8; ++i) rsv[i] = __builtin_amdgcn_rsqf(rsv[i] * (1.0f / 1024.0f) + EPS);
; #pragma unroll
;         for (int ai = 0; ai < 2; ++ai)
; #pragma unroll
;             for (int m = 0; m < 4; ++m) {
;                 const int row = row0 + ai * HALF + m * 16;
;                 const float rs = rsv[ai * 4 + m], c1 = -rs * LOG2E, rs2 = rs * rs;
;                 float h[8];
; #pragma unroll
;                 for (int n = 0; n < 2; ++n)
; #pragma unroll
;                     for (int i = 0; i < 4; ++i) {
;                         const float g = acc[ai][0][m][n][i], uu = acc[ai][1][m][n][i];
;                         const float e = __builtin_amdgcn_exp2f(g * c1);
;                         h[n * 4 + i] = (g * uu) * (rs2 * __builtin_amdgcn_rcpf(1.0f + e));
;                     }
;                 u32x4 w; w.x = cvt_pk_bf16(h[0], h[1]); w.y = cvt_pk_bf16(h[2], h[3]); w.z = cvt_pk_bf16(h[4], h[5]); w.w = cvt_pk_bf16(h[6], h[7]);
;                 *(GAS u32x4*)(H + (size_t)row * FF + col0) = w;
;                 asm volatile("" ::: "memory");
;             }
.LBB0_165:
	v_lshl_add_u32 v144, s22, 8, v146
	v_mov_b32_e32 v145, v235
	v_mov_b32_e32 v164, v236
	v_mov_b32_e32 v165, v237
	v_mov_b32_e32 v166, v238
	v_mov_b32_e32 v167, v239
	v_mov_b32_e32 v168, v240
	v_mov_b32_e32 v169, v241
	v_mov_b32_e32 v170, v242
	v_lshl_or_b32 v156, s15, 7, v148
	v_pk_mul_f32 v[160:161], v[112:113], v[120:121]
	v_mov_b64_e32 v[120:121], s[6:7]
	v_ashrrev_i32_e32 v157, 31, v156
	v_pk_mul_f32 v[158:159], v[114:115], v[122:123]
	v_pk_mul_f32 v[162:163], v[110:111], v[106:107]
	v_mad_i64_i32 v[122:123], s[24:25], v144, s56, v[120:121]
	v_lshlrev_b64 v[106:107], 1, v[156:157]
	v_lshl_add_u64 v[156:157], v[122:123], 0, v[106:107]
	v_pk_mul_f32 v[126:127], v[118:119], v[126:127]
	v_pk_mul_f32 v[124:125], v[116:117], v[124:125]
	v_pk_mul_f32 v[98:99], v[102:103], v[98:99]
	v_pk_mul_f32 v[104:105], v[108:109], v[104:105]
	v_pk_mul_f32 v[96:97], v[100:101], v[96:97]
	v_pk_mul_f32 v[90:91], v[94:95], v[90:91]
	v_pk_mul_f32 v[88:89], v[92:93], v[88:89]
	v_pk_mul_f32 v[82:83], v[86:87], v[82:83]
	v_pk_mul_f32 v[80:81], v[84:85], v[80:81]
	v_pk_mul_f32 v[74:75], v[78:79], v[74:75]
	v_pk_mul_f32 v[72:73], v[76:77], v[72:73]
	v_pk_mul_f32 v[66:67], v[70:71], v[66:67]
	v_pk_mul_f32 v[64:65], v[68:69], v[64:65]
	v_pk_mul_f32 v[58:59], v[62:63], v[58:59]
	v_pk_mul_f32 v[56:57], v[60:61], v[56:57]
	v_pk_mul_f32 v[50:51], v[54:55], v[50:51]
	v_pk_mul_f32 v[48:49], v[52:53], v[48:49]
	v_add_u32_e32 v171, 0x80, v144
	v_pk_mul_f32 v[42:43], v[46:47], v[42:43]
	v_pk_mul_f32 v[40:41], v[44:45], v[40:41]
	v_pk_mul_f32 v[34:35], v[38:39], v[34:35]
	v_pk_mul_f32 v[32:33], v[36:37], v[32:33]
	v_pk_mul_f32 v[26:27], v[30:31], v[26:27]
	v_pk_mul_f32 v[24:25], v[28:29], v[24:25]
	v_pk_mul_f32 v[18:19], v[22:23], v[18:19]
	v_pk_mul_f32 v[16:17], v[20:21], v[16:17]
	v_pk_mul_f32 v[10:11], v[14:15], v[10:11]
	v_pk_mul_f32 v[8:9], v[12:13], v[8:9]
	v_pk_mul_f32 v[2:3], v[6:7], v[2:3]
	v_pk_mul_f32 v[0:1], v[4:5], v[0:1]
	s_andn2_b64 vcc, exec, s[0:1]
	s_mov_b64 s[0:1], -1
	s_waitcnt lgkmcnt(0)
	v_fmamk_f32 v122, v145, 0x3a800000, v153
	v_fmamk_f32 v123, v164, 0x3a800000, v153
	v_fmamk_f32 v145, v165, 0x3a800000, v153
	v_fmamk_f32 v164, v166, 0x3a800000, v153
	v_fmamk_f32 v165, v167, 0x3a800000, v153
	v_fmamk_f32 v166, v168, 0x3a800000, v153
	v_fmamk_f32 v167, v169, 0x3a800000, v153
	v_rsq_f32_e32 v169, v122
	v_fmamk_f32 v168, v170, 0x3a800000, v153
	v_rsq_f32_e32 v170, v123
	v_rsq_f32_e32 v123, v167
	v_mul_f32_e32 v167, 0xbfb8aa3b, v169
	v_mul_f32_e32 v116, v116, v167
	v_mul_f32_e32 v174, 0xbfb8aa3b, v170
	v_mul_f32_e32 v117, v117, v167
	v_mul_f32_e32 v118, v118, v167
	v_mul_f32_e32 v119, v119, v167
	v_mul_f32_e32 v112, v112, v167
	v_mul_f32_e32 v113, v113, v167
	v_mul_f32_e32 v114, v114, v167
	v_mul_f32_e32 v115, v115, v167
	v_mul_f32_e32 v110, v110, v174
	v_exp_f32_e32 v116, v116
	v_exp_f32_e32 v117, v117
	v_exp_f32_e32 v118, v118
	v_exp_f32_e32 v119, v119
	v_exp_f32_e32 v112, v112
	v_exp_f32_e32 v113, v113
	v_exp_f32_e32 v114, v114
	v_exp_f32_e32 v115, v115
	v_exp_f32_e32 v110, v110
	v_mul_f32_e32 v111, v111, v174
	v_rsq_f32_e32 v172, v164
	v_rsq_f32_e32 v173, v166
	v_mul_f32_e32 v164, v169, v169
	v_mul_f32_e32 v166, v170, v170
	v_exp_f32_e32 v169, v111
	v_add_f32_e32 v111, 1.0, v116
	v_add_f32_e32 v116, 1.0, v117
	v_add_f32_e32 v117, 1.0, v118
	v_add_f32_e32 v118, 1.0, v119
	v_add_f32_e32 v119, 1.0, v112
	v_add_f32_e32 v170, 1.0, v113
	v_add_f32_e32 v175, 1.0, v114
	v_add_f32_e32 v176, 1.0, v115
	v_rsq_f32_e32 v165, v165
	v_add_f32_e32 v177, 1.0, v110
	v_rcp_f32_e32 v110, v111
	v_rcp_f32_e32 v111, v116
	v_rcp_f32_e32 v112, v117
	v_rcp_f32_e32 v113, v118
	v_rcp_f32_e32 v114, v119
	v_rcp_f32_e32 v115, v170
	v_rcp_f32_e32 v116, v175
	v_rcp_f32_e32 v117, v176
	v_pk_mul_f32 v[110:111], v[164:165], v[110:111] op_sel_hi:[0,1]
	v_pk_mul_f32 v[112:113], v[164:165], v[112:113] op_sel_hi:[0,1]
	v_pk_mul_f32 v[114:115], v[164:165], v[114:115] op_sel_hi:[0,1]
	v_pk_mul_f32 v[116:117], v[164:165], v[116:117] op_sel_hi:[0,1]
	v_pk_mul_f32 v[110:111], v[124:125], v[110:111]
	v_pk_mul_f32 v[112:113], v[126:127], v[112:113]
	v_pk_mul_f32 v[114:115], v[160:161], v[114:115]
	v_pk_mul_f32 v[116:117], v[158:159], v[116:117]
	v_cvt_pk_bf16_f32 v110, v110, v111
	v_cvt_pk_bf16_f32 v111, v112, v113
	v_cvt_pk_bf16_f32 v112, v114, v115
	v_cvt_pk_bf16_f32 v113, v116, v117
	global_store_dwordx4 v[156:157], v[110:113], off
	v_rsq_f32_e32 v122, v168
	v_mul_f32_e32 v167, v108, v174
	v_add_f32_e32 v110, 1.0, v169
	v_mul_f32_e32 v168, v109, v174
	v_rcp_f32_e32 v169, v110
	v_mul_f32_e32 v110, v100, v174
	v_mul_f32_e32 v111, v101, v174
	v_exp_f32_e32 v167, v167
	v_exp_f32_e32 v168, v168
	v_exp_f32_e32 v110, v110
	v_exp_f32_e32 v111, v111
	v_mul_f32_e32 v112, v102, v174
	v_mul_f32_e32 v113, v103, v174
	v_exp_f32_e32 v112, v112
	v_exp_f32_e32 v113, v113
	v_add_f32_e32 v167, 1.0, v167
	v_add_f32_e32 v168, 1.0, v168
	v_add_f32_e32 v110, 1.0, v110
	v_add_f32_e32 v111, 1.0, v111
	v_rcp_f32_e32 v118, v167
	v_rcp_f32_e32 v119, v168
	v_rcp_f32_e32 v110, v110
	v_rcp_f32_e32 v111, v111
	v_add_f32_e32 v102, 1.0, v112
	v_add_f32_e32 v103, 1.0, v113
	v_rcp_f32_e32 v168, v177
	v_rcp_f32_e32 v102, v102
	v_rcp_f32_e32 v103, v103
	v_rsq_f32_e32 v145, v145
	v_pk_mul_f32 v[108:109], v[166:167], v[118:119] op_sel_hi:[0,1]
	v_pk_mul_f32 v[100:101], v[166:167], v[110:111] op_sel_hi:[0,1]
	v_pk_mul_f32 v[104:105], v[104:105], v[108:109]
	v_pk_mul_f32 v[108:109], v[166:167], v[168:169] op_sel_hi:[0,1]
	v_pk_mul_f32 v[100:101], v[96:97], v[100:101]
	v_pk_mul_f32 v[96:97], v[166:167], v[102:103] op_sel_hi:[0,1]
	v_or_b32_e32 v110, 16, v144
	v_pk_mul_f32 v[108:109], v[162:163], v[108:109]
; #define GAS __attribute__((address_space(1)))
; __device__ __forceinline__ unsigned cvt_pk_bf16(float lo, float hi) { f32x2_t v = {lo, hi}; bf16x2_t b = __builtin_convertvector(v, bf16x2_t); return __builtin_bit_cast(unsigned, b); }
;     __device__ __forceinline__ void operator()(const f32x4 (&acc)[2][2][4][2], const Unit& u, int wr, int wc, int fr, int fq) const {
;     ...
;         for (int ai = 0; ai < 2; ++ai)
; #pragma unroll
;             for (int m = 0; m < 4; ++m) {
;                 const int row = row0 + ai * HALF + m * 16;
;                 const float rs = rsv[ai * 4 + m], c1 = -rs * LOG2E, rs2 = rs * rs;
;                 float h[8];
; #pragma unroll
;                 for (int n = 0; n < 2; ++n)
; #pragma unroll
;                     for (int i = 0; i < 4; ++i) {
;                         const float g = acc[ai][0][m][n][i], uu = acc[ai][1][m][n][i];
;                         const float e = __builtin_amdgcn_exp2f(g * c1);
;                         h[n * 4 + i] = (g * uu) * (rs2 * __builtin_amdgcn_rcpf(1.0f + e));
;                     }
;                 u32x4 w; w.x = cvt_pk_bf16(h[0], h[1]); w.y = cvt_pk_bf16(h[2], h[3]); w.z = cvt_pk_bf16(h[4], h[5]); w.w = cvt_pk_bf16(h[6], h[7]);
;                 *(GAS u32x4*)(H + (size_t)row * FF + col0) = w;
;                 asm volatile("" ::: "memory");
;             }
	v_pk_mul_f32 v[102:103], v[98:99], v[96:97]
	v_cvt_pk_bf16_f32 v98, v100, v101
	v_mad_i64_i32 v[100:101], s[24:25], v110, s56, v[120:121]
	v_cvt_pk_bf16_f32 v96, v104, v105
	v_cvt_pk_bf16_f32 v97, v108, v109
	v_cvt_pk_bf16_f32 v99, v102, v103
	v_lshl_add_u64 v[100:101], v[100:101], 0, v[106:107]
	global_store_dwordx4 v[100:101], v[96:99], off
	s_nop 1
	v_mul_f32_e32 v97, 0xbfb8aa3b, v145
	v_mul_f32_e32 v96, v92, v97
	v_exp_f32_e32 v98, v96
	v_mul_f32_e32 v96, v93, v97
	v_exp_f32_e32 v99, v96
	v_mul_f32_e32 v100, v94, v97
	v_mul_f32_e32 v101, v95, v97
	v_exp_f32_e32 v100, v100
	v_exp_f32_e32 v101, v101
	v_add_f32_e32 v98, 1.0, v98
	v_add_f32_e32 v99, 1.0, v99
	v_rcp_f32_e32 v98, v98
	v_rcp_f32_e32 v99, v99
	v_add_f32_e32 v94, 1.0, v100
	v_add_f32_e32 v95, 1.0, v101
	v_rcp_f32_e32 v94, v94
	v_rcp_f32_e32 v95, v95
	v_mul_f32_e32 v96, v145, v145
	v_pk_mul_f32 v[92:93], v[96:97], v[98:99] op_sel_hi:[0,1]
	v_pk_mul_f32 v[88:89], v[88:89], v[92:93]
	v_pk_mul_f32 v[92:93], v[96:97], v[94:95] op_sel_hi:[0,1]
	v_mul_f32_e32 v94, v84, v97
	v_mul_f32_e32 v95, v85, v97
	v_exp_f32_e32 v94, v94
	v_exp_f32_e32 v95, v95
	v_pk_mul_f32 v[90:91], v[90:91], v[92:93]
	v_add_f32_e32 v92, 1.0, v94
	v_add_f32_e32 v93, 1.0, v95
	v_mul_f32_e32 v94, v86, v97
	v_mul_f32_e32 v95, v87, v97
	v_exp_f32_e32 v94, v94
	v_exp_f32_e32 v95, v95
	v_rcp_f32_e32 v92, v92
	v_rcp_f32_e32 v93, v93
	v_add_f32_e32 v86, 1.0, v94
	v_add_f32_e32 v87, 1.0, v95
	v_rcp_f32_e32 v86, v86
	v_rcp_f32_e32 v87, v87
	v_pk_mul_f32 v[84:85], v[96:97], v[92:93] op_sel_hi:[0,1]
	v_pk_mul_f32 v[84:85], v[80:81], v[84:85]
	v_or_b32_e32 v92, 32, v144
	v_pk_mul_f32 v[80:81], v[96:97], v[86:87] op_sel_hi:[0,1]
	v_pk_mul_f32 v[86:87], v[82:83], v[80:81]
	v_cvt_pk_bf16_f32 v82, v84, v85
	v_mad_i64_i32 v[84:85], s[24:25], v92, s56, v[120:121]
	v_cvt_pk_bf16_f32 v80, v88, v89
	v_cvt_pk_bf16_f32 v81, v90, v91
	v_cvt_pk_bf16_f32 v83, v86, v87
	v_lshl_add_u64 v[84:85], v[84:85], 0, v[106:107]
	global_store_dwordx4 v[84:85], v[80:83], off
	s_nop 1
	v_mul_f32_e32 v81, 0xbfb8aa3b, v172
	v_mul_f32_e32 v80, v76, v81
	v_exp_f32_e32 v82, v80
	v_mul_f32_e32 v80, v77, v81
	v_exp_f32_e32 v83, v80
	v_mul_f32_e32 v84, v78, v81
	v_mul_f32_e32 v85, v79, v81
	v_exp_f32_e32 v84, v84
	v_exp_f32_e32 v85, v85
	v_add_f32_e32 v82, 1.0, v82
	v_add_f32_e32 v83, 1.0, v83
	v_rcp_f32_e32 v82, v82
	v_rcp_f32_e32 v83, v83
	v_add_f32_e32 v78, 1.0, v84
	v_add_f32_e32 v79, 1.0, v85
	v_rcp_f32_e32 v78, v78
	v_rcp_f32_e32 v79, v79
	v_mul_f32_e32 v80, v172, v172
	v_pk_mul_f32 v[76:77], v[80:81], v[82:83] op_sel_hi:[0,1]
	v_pk_mul_f32 v[72:73], v[72:73], v[76:77]
	v_pk_mul_f32 v[76:77], v[80:81], v[78:79] op_sel_hi:[0,1]
	v_mul_f32_e32 v78, v68, v81
	v_mul_f32_e32 v79, v69, v81
	v_exp_f32_e32 v78, v78
	v_exp_f32_e32 v79, v79
	v_pk_mul_f32 v[74:75], v[74:75], v[76:77]
	v_add_f32_e32 v76, 1.0, v78
	v_add_f32_e32 v77, 1.0, v79
	v_mul_f32_e32 v78, v70, v81
	v_mul_f32_e32 v79, v71, v81
	v_exp_f32_e32 v78, v78
	v_exp_f32_e32 v79, v79
	v_rcp_f32_e32 v76, v76
	v_rcp_f32_e32 v77, v77
	v_add_f32_e32 v70, 1.0, v78
	v_add_f32_e32 v71, 1.0, v79
	v_rcp_f32_e32 v70, v70
	v_rcp_f32_e32 v71, v71
	v_pk_mul_f32 v[68:69], v[80:81], v[76:77] op_sel_hi:[0,1]
	v_pk_mul_f32 v[68:69], v[64:65], v[68:69]
	v_or_b32_e32 v76, 48, v144
	v_pk_mul_f32 v[64:65], v[80:81], v[70:71] op_sel_hi:[0,1]
	v_pk_mul_f32 v[70:71], v[66:67], v[64:65]
	v_cvt_pk_bf16_f32 v66, v68, v69
	v_mad_i64_i32 v[68:69], s[24:25], v76, s56, v[120:121]
	v_cvt_pk_bf16_f32 v64, v72, v73
	v_cvt_pk_bf16_f32 v65, v74, v75
	v_cvt_pk_bf16_f32 v67, v70, v71
	v_lshl_add_u64 v[68:69], v[68:69], 0, v[106:107]
	global_store_dwordx4 v[68:69], v[64:67], off
	s_nop 1
	v_mul_f32_e32 v65, 0xbfb8aa3b, v165
	v_mul_f32_e32 v64, v60, v65
	v_exp_f32_e32 v66, v64
	v_mul_f32_e32 v64, v61, v65
	v_exp_f32_e32 v67, v64
	v_mul_f32_e32 v68, v62, v65
	v_mul_f32_e32 v69, v63, v65
	v_exp_f32_e32 v68, v68
	v_exp_f32_e32 v69, v69
	v_add_f32_e32 v66, 1.0, v66
	v_add_f32_e32 v67, 1.0, v67
	v_rcp_f32_e32 v66, v66
	v_rcp_f32_e32 v67, v67
	v_add_f32_e32 v62, 1.0, v68
	v_add_f32_e32 v63, 1.0, v69
	v_rcp_f32_e32 v62, v62
	v_rcp_f32_e32 v63, v63
	v_mul_f32_e32 v64, v165, v165
	v_pk_mul_f32 v[60:61], v[64:65], v[66:67] op_sel_hi:[0,1]
	v_pk_mul_f32 v[56:57], v[56:57], v[60:61]
	v_pk_mul_f32 v[60:61], v[64:65], v[62:63] op_sel_hi:[0,1]
	v_mul_f32_e32 v62, v52, v65
	v_mul_f32_e32 v63, v53, v65
	v_exp_f32_e32 v62, v62
	v_exp_f32_e32 v63, v63
	v_pk_mul_f32 v[58:59], v[58:59], v[60:61]
	v_add_f32_e32 v60, 1.0, v62
	v_add_f32_e32 v61, 1.0, v63
	v_mul_f32_e32 v62, v54, v65
	v_mul_f32_e32 v63, v55, v65
	v_exp_f32_e32 v62, v62
	v_exp_f32_e32 v63, v63
	v_rcp_f32_e32 v60, v60
	v_rcp_f32_e32 v61, v61
	v_add_f32_e32 v54, 1.0, v62
	v_add_f32_e32 v55, 1.0, v63
	v_rcp_f32_e32 v54, v54
	v_rcp_f32_e32 v55, v55
	v_pk_mul_f32 v[52:53], v[64:65], v[60:61] op_sel_hi:[0,1]
	v_pk_mul_f32 v[52:53], v[48:49], v[52:53]
	v_pk_mul_f32 v[48:49], v[64:65], v[54:55] op_sel_hi:[0,1]
	v_pk_mul_f32 v[54:55], v[50:51], v[48:49]
	v_cvt_pk_bf16_f32 v50, v52, v53
	v_mad_i64_i32 v[52:53], s[24:25], v171, s56, v[120:121]
	v_cvt_pk_bf16_f32 v48, v56, v57
	v_cvt_pk_bf16_f32 v49, v58, v59
; #define GAS __attribute__((address_space(1)))
; __device__ __forceinline__ unsigned cvt_pk_bf16(float lo, float hi) { f32x2_t v = {lo, hi}; bf16x2_t b = __builtin_convertvector(v, bf16x2_t); return __builtin_bit_cast(unsigned, b); }
; #define PG8_BAR __builtin_amdgcn_s_barrier()
;     __device__ __forceinline__ void operator()(const f32x4 (&acc)[2][2][4][2], const Unit& u, int wr, int wc, int fr, int fq) const {
;     ...
;         for (int ai = 0; ai < 2; ++ai)
; #pragma unroll
;             for (int m = 0; m < 4; ++m) {
;                 const int row = row0 + ai * HALF + m * 16;
;                 const float rs = rsv[ai * 4 + m], c1 = -rs * LOG2E, rs2 = rs * rs;
;                 float h[8];
; #pragma unroll
;                 for (int n = 0; n < 2; ++n)
; #pragma unroll
;                     for (int i = 0; i < 4; ++i) {
;                         const float g = acc[ai][0][m][n][i], uu = acc[ai][1][m][n][i];
;                         const float e = __builtin_amdgcn_exp2f(g * c1);
;                         h[n * 4 + i] = (g * uu) * (rs2 * __builtin_amdgcn_rcpf(1.0f + e));
;                     }
;                 u32x4 w; w.x = cvt_pk_bf16(h[0], h[1]); w.y = cvt_pk_bf16(h[2], h[3]); w.z = cvt_pk_bf16(h[4], h[5]); w.w = cvt_pk_bf16(h[6], h[7]);
;                 *(GAS u32x4*)(H + (size_t)row * FF + col0) = w;
;                 asm volatile("" ::: "memory");
;             }
; template <class Epi>
; __device__ __forceinline__ void gemm_phase(LAS unsigned char* lds, const Gemm g, const StaticOrder& S, const Epi& E) {
;     ...
;         if (wr == 0) PG8_BAR;
;         E(acc, cur, wr, wc, fr, fq);
;         if (!has_next) break;
; #pragma unroll
;         for (int a = 0; a < 2; ++a)
; #pragma unroll
;             for (int b = 0; b < 2; ++b)
; #pragma unroll
;                 for (int m = 0; m < 4; ++m)
; #pragma unroll
;                     for (int n = 0; n < 2; ++n) acc[a][b][m][n] = (f32x4){0.f, 0.f, 0.f, 0.f};
;         cur = nxt; cA = nA; cB = nB; ++ui;
;         if (wr == 1) PG8_BAR;
	v_cvt_pk_bf16_f32 v51, v54, v55
	v_lshl_add_u64 v[52:53], v[52:53], 0, v[106:107]
	global_store_dwordx4 v[52:53], v[48:51], off
	s_nop 1
	v_mul_f32_e32 v49, 0xbfb8aa3b, v173
	v_mul_f32_e32 v48, v44, v49
	v_exp_f32_e32 v50, v48
	v_mul_f32_e32 v48, v45, v49
	v_exp_f32_e32 v51, v48
	v_mul_f32_e32 v52, v46, v49
	v_mul_f32_e32 v53, v47, v49
	v_exp_f32_e32 v52, v52
	v_exp_f32_e32 v53, v53
	v_add_f32_e32 v50, 1.0, v50
	v_add_f32_e32 v51, 1.0, v51
	v_rcp_f32_e32 v50, v50
	v_rcp_f32_e32 v51, v51
	v_add_f32_e32 v46, 1.0, v52
	v_add_f32_e32 v47, 1.0, v53
	v_rcp_f32_e32 v46, v46
	v_rcp_f32_e32 v47, v47
	v_mul_f32_e32 v48, v173, v173
	v_pk_mul_f32 v[44:45], v[48:49], v[50:51] op_sel_hi:[0,1]
	v_pk_mul_f32 v[40:41], v[40:41], v[44:45]
	v_pk_mul_f32 v[44:45], v[48:49], v[46:47] op_sel_hi:[0,1]
	v_mul_f32_e32 v46, v36, v49
	v_mul_f32_e32 v47, v37, v49
	v_exp_f32_e32 v46, v46
	v_exp_f32_e32 v47, v47
	v_pk_mul_f32 v[42:43], v[42:43], v[44:45]
	v_add_f32_e32 v44, 1.0, v46
	v_add_f32_e32 v45, 1.0, v47
	v_mul_f32_e32 v46, v38, v49
	v_mul_f32_e32 v47, v39, v49
	v_exp_f32_e32 v46, v46
	v_exp_f32_e32 v47, v47
	v_rcp_f32_e32 v44, v44
	v_rcp_f32_e32 v45, v45
	v_add_f32_e32 v38, 1.0, v46
	v_add_f32_e32 v39, 1.0, v47
	v_rcp_f32_e32 v38, v38
	v_rcp_f32_e32 v39, v39
	v_pk_mul_f32 v[36:37], v[48:49], v[44:45] op_sel_hi:[0,1]
	v_pk_mul_f32 v[36:37], v[32:33], v[36:37]
	v_add_u32_e32 v44, 0x90, v144
	v_pk_mul_f32 v[32:33], v[48:49], v[38:39] op_sel_hi:[0,1]
	v_pk_mul_f32 v[38:39], v[34:35], v[32:33]
	v_cvt_pk_bf16_f32 v34, v36, v37
	v_mad_i64_i32 v[36:37], s[24:25], v44, s56, v[120:121]
	v_cvt_pk_bf16_f32 v32, v40, v41
	v_cvt_pk_bf16_f32 v33, v42, v43
	v_cvt_pk_bf16_f32 v35, v38, v39
	v_lshl_add_u64 v[36:37], v[36:37], 0, v[106:107]
	global_store_dwordx4 v[36:37], v[32:35], off
	s_nop 1
	v_mul_f32_e32 v33, 0xbfb8aa3b, v123
	v_mul_f32_e32 v32, v28, v33
	v_exp_f32_e32 v34, v32
	v_mul_f32_e32 v32, v29, v33
	v_exp_f32_e32 v35, v32
	v_mul_f32_e32 v36, v30, v33
	v_mul_f32_e32 v37, v31, v33
	v_exp_f32_e32 v36, v36
	v_exp_f32_e32 v37, v37
	v_add_f32_e32 v34, 1.0, v34
	v_add_f32_e32 v35, 1.0, v35
	v_rcp_f32_e32 v34, v34
	v_rcp_f32_e32 v35, v35
	v_add_f32_e32 v30, 1.0, v36
	v_add_f32_e32 v31, 1.0, v37
	v_rcp_f32_e32 v30, v30
	v_rcp_f32_e32 v31, v31
	v_mul_f32_e32 v32, v123, v123
	v_pk_mul_f32 v[28:29], v[32:33], v[34:35] op_sel_hi:[0,1]
	v_pk_mul_f32 v[24:25], v[24:25], v[28:29]
	v_pk_mul_f32 v[28:29], v[32:33], v[30:31] op_sel_hi:[0,1]
	v_mul_f32_e32 v30, v20, v33
	v_mul_f32_e32 v31, v21, v33
	v_exp_f32_e32 v30, v30
	v_exp_f32_e32 v31, v31
	v_pk_mul_f32 v[26:27], v[26:27], v[28:29]
	v_add_f32_e32 v28, 1.0, v30
	v_add_f32_e32 v29, 1.0, v31
	v_mul_f32_e32 v30, v22, v33
	v_mul_f32_e32 v31, v23, v33
	v_exp_f32_e32 v30, v30
	v_exp_f32_e32 v31, v31
	v_rcp_f32_e32 v28, v28
	v_rcp_f32_e32 v29, v29
	v_add_f32_e32 v22, 1.0, v30
	v_add_f32_e32 v23, 1.0, v31
	v_rcp_f32_e32 v22, v22
	v_rcp_f32_e32 v23, v23
	v_pk_mul_f32 v[20:21], v[32:33], v[28:29] op_sel_hi:[0,1]
	v_pk_mul_f32 v[20:21], v[16:17], v[20:21]
	v_add_u32_e32 v28, 0xa0, v144
	v_pk_mul_f32 v[16:17], v[32:33], v[22:23] op_sel_hi:[0,1]
	v_pk_mul_f32 v[22:23], v[18:19], v[16:17]
	v_cvt_pk_bf16_f32 v18, v20, v21
	v_mad_i64_i32 v[20:21], s[24:25], v28, s56, v[120:121]
	v_cvt_pk_bf16_f32 v16, v24, v25
	v_cvt_pk_bf16_f32 v17, v26, v27
	v_cvt_pk_bf16_f32 v19, v22, v23
	v_lshl_add_u64 v[20:21], v[20:21], 0, v[106:107]
	global_store_dwordx4 v[20:21], v[16:19], off
	s_nop 1
	v_mul_f32_e32 v17, 0xbfb8aa3b, v122
	v_mul_f32_e32 v16, v12, v17
	v_exp_f32_e32 v18, v16
	v_mul_f32_e32 v16, v13, v17
	v_exp_f32_e32 v19, v16
	v_mul_f32_e32 v20, v14, v17
	v_mul_f32_e32 v21, v15, v17
	v_exp_f32_e32 v20, v20
	v_exp_f32_e32 v21, v21
	v_add_f32_e32 v18, 1.0, v18
	v_add_f32_e32 v19, 1.0, v19
	v_rcp_f32_e32 v18, v18
	v_rcp_f32_e32 v19, v19
	v_add_f32_e32 v14, 1.0, v20
	v_add_f32_e32 v15, 1.0, v21
	v_rcp_f32_e32 v14, v14
	v_rcp_f32_e32 v15, v15
	v_mul_f32_e32 v16, v122, v122
	v_pk_mul_f32 v[12:13], v[16:17], v[18:19] op_sel_hi:[0,1]
	v_pk_mul_f32 v[8:9], v[8:9], v[12:13]
	v_pk_mul_f32 v[12:13], v[16:17], v[14:15] op_sel_hi:[0,1]
	v_mul_f32_e32 v14, v4, v17
	v_mul_f32_e32 v15, v5, v17
	v_exp_f32_e32 v14, v14
	v_exp_f32_e32 v15, v15
	v_pk_mul_f32 v[10:11], v[10:11], v[12:13]
	v_add_f32_e32 v12, 1.0, v14
	v_add_f32_e32 v13, 1.0, v15
	v_mul_f32_e32 v14, v6, v17
	v_mul_f32_e32 v15, v7, v17
	v_exp_f32_e32 v14, v14
	v_exp_f32_e32 v15, v15
	v_rcp_f32_e32 v12, v12
	v_rcp_f32_e32 v13, v13
	v_add_f32_e32 v6, 1.0, v14
	v_add_f32_e32 v7, 1.0, v15
	v_rcp_f32_e32 v6, v6
	v_rcp_f32_e32 v7, v7
	v_pk_mul_f32 v[4:5], v[16:17], v[12:13] op_sel_hi:[0,1]
	v_pk_mul_f32 v[4:5], v[0:1], v[4:5]
	v_add_u32_e32 v12, 0xb0, v144
	v_pk_mul_f32 v[0:1], v[16:17], v[6:7] op_sel_hi:[0,1]
	v_pk_mul_f32 v[6:7], v[2:3], v[0:1]
	v_cvt_pk_bf16_f32 v2, v4, v5
	v_mad_i64_i32 v[4:5], s[24:25], v12, s56, v[120:121]
	v_cvt_pk_bf16_f32 v0, v8, v9
	v_cvt_pk_bf16_f32 v1, v10, v11
	v_cvt_pk_bf16_f32 v3, v6, v7
	v_lshl_add_u64 v[4:5], v[4:5], 0, v[106:107]
	global_store_dwordx4 v[4:5], v[0:3], off
	s_cbranch_vccnz .LBB0_158
	s_andn2_b64 vcc, exec, s[4:5]
	s_cbranch_vccnz .LBB0_157
	s_barrier
	s_branch .LBB0_157

; #define PG8_STAGE(bufoff, gbase, voff) do { _Pragma("unroll") for (int _i = 0; _i < 2; ++_i) \
;         __builtin_amdgcn_global_load_lds((const unsigned*)((const char*)(gbase) + (voff)[_i]), (LAS unsigned*)(lds + (bufoff) + ldsw + _i * 8192), 16, 0, 0); } while (0)
; #define PG8_WAIT_V(n) asm volatile("s_waitcnt vmcnt(" #n ")" ::: "memory")
; #define PG8_BAR __builtin_amdgcn_s_barrier()
; template <class Epi>
; __device__ __forceinline__ void gemm_phase(LAS unsigned char* lds, const Gemm g, const StaticOrder& S, const Epi& E) {
;     ...
;     const int tid = tid_, wid = __builtin_amdgcn_readfirstlane(tid >> 6), lane = tid & 63, wr = wid >> 2, wc = wid & 3, fr = lane & 15, fq = lane >> 4;
;     const int K = g.K, nt = K / BK, lda = g.lda;
;     unsigned voffA[2], voffB[2];
; #pragma unroll
;     for (int i = 0; i < 2; ++i) { int R, C; stage_rc(tid * 16 + i * 8192, R, C); const int Rb = (R & ~31) + perm32(R & 31);
;         voffA[i] = (unsigned)(R * lda + C) * 2u; voffB[i] = (unsigned)(Rb * K + C) * 2u; }
;     const unsigned kstep = (unsigned)(BK * 2);
;     const unsigned hstepA = (unsigned)(HALF * lda * 2), hstepB = (unsigned)(HALF * K * 2);
;     const size_t tstepA = 2 * (size_t)hstepA, tstepB = 2 * (size_t)hstepB;
;     const unsigned ldsw = (unsigned)wid * 1024u;
;     const int aoff = lds_byte(wr * 64 + fr, fq * 8), boff = lds_byte(wc * 32 + fr, fq * 8);
;     ...
;     Unit cur, nxt; int ui = 0;
;     if (!S.next(0, cur)) return;
;     f32x4 acc[2][2][4][2];
; #pragma unroll
;     for (int a = 0; a < 2; ++a)
; #pragma unroll
;         for (int b = 0; b < 2; ++b)
; #pragma unroll
;             for (int m = 0; m < 4; ++m)
; #pragma unroll
;                 for (int n = 0; n < 2; ++n) acc[a][b][m][n] = (f32x4){0.f, 0.f, 0.f, 0.f};
;     bf16x8 At[4][2], B0[2][2], B1[2][2];
;     const char* cA = (const char*)g.A + (size_t)cur.pm * tstepA; const char* cB = (const char*)g.Bt + (size_t)cur.pn * tstepB;
;     PG8_STAGE(PG8_SB(0, 0), cB, voffB); PG8_STAGE(PG8_SB(0, 1), cB + hstepB, voffB); PG8_STAGE(PG8_SA(0, 0), cA, voffA); PG8_STAGE(PG8_SA(0, 1), cA + hstepA, voffA);
;     if (wr == 1) PG8_BAR;
;     PG8_WAIT_V(2); PG8_BAR;
;     PG8_STAGE(PG8_SB(1, 0), cB + kstep, voffB); PG8_STAGE(PG8_SA(1, 0), cA + kstep, voffA); PG8_STAGE(PG8_SB(1, 1), cB + hstepB + kstep, voffB);
;     PG8_WAIT_V(6); PG8_BAR;
.LBB0_694:
	s_or_b64 exec, exec, s[46:47]
	s_mov_b64 s[6:7], s[42:43]
	v_mov_b32_e32 v9, v154
	v_cndmask_b32_e64 v0, 0, 1, s[38:39]
	s_waitcnt lgkmcnt(0)
	s_barrier
	s_cselect_b32 s92, 1, 0
	s_cmp_lt_u32 s14, 128
	s_cbranch_scc1 .Lstg_2
	s_sleep 127
	s_sleep 127
	s_sleep 127
	s_sleep 127
	s_sleep 127
.Lstg_2:
	s_cmp_lg_u32 s92, 0
	v_cmp_ne_u32_e64 s[2:3], 1, v0
	s_andn2_b64 vcc, exec, s[38:39]
	v_readfirstlane_b32 s17, v9
	s_cbranch_vccnz .LBB0_710
	v_lshlrev_b32_e32 v0, 4, v9
	v_add_u32_e32 v1, 0x2000, v0
	v_ashrrev_i32_e32 v2, 31, v1
	v_lshrrev_b32_e32 v2, 22, v2
	v_add_u32_e32 v2, v1, v2
	v_ashrrev_i32_e32 v8, 10, v2
	v_mul_i32_i24_e32 v2, 0x400, v8
	v_sub_u32_e32 v1, v1, v2
	v_lshrrev_b32_e32 v2, 4, v1
	v_bitop3_b32 v1, v2, v1, 32 bitop3:0x6c
	v_ashrrev_i32_e32 v2, 31, v1
	v_lshrrev_b32_e32 v2, 26, v2
	v_add_u32_e32 v2, v1, v2
	v_lshlrev_b32_e32 v3, 3, v8
	v_ashrrev_i32_e32 v10, 6, v2
	v_and_b32_e32 v3, -16, v3
	v_add_u32_e32 v3, v10, v3
	v_and_b32_e32 v4, 3, v10
	s_mov_b32 s8, 0x1fffe0
	v_lshrrev_b32_e32 v5, 2, v3
	v_lshlrev_b32_e32 v6, 1, v3
	v_and_b32_e32 v2, 0xc0, v2
	v_and_or_b32 v4, v3, s8, v4
	v_and_b32_e32 v5, 4, v5
	v_and_b32_e32 v6, 24, v6
	v_sub_u32_e32 v1, v1, v2
	v_mov_b32_e32 v2, 1
	v_or3_b32 v4, v4, v5, v6
	v_lshlrev_b32_e32 v5, 5, v8
	v_ashrrev_i16_sdwa v1, v2, sext(v1) dst_sel:DWORD dst_unused:UNUSED_PAD src0_sel:DWORD src1_sel:BYTE_0
	v_and_b32_e32 v5, 32, v5
	v_bfe_i32 v11, v1, 0, 16
	v_add_lshl_u32 v1, v5, v11, 1
	v_lshl_add_u32 v128, v4, 11, v1
	v_lshl_add_u32 v130, v3, 11, v1
	v_bfe_i32 v1, v9, 27, 1
	v_lshrrev_b32_e32 v1, 22, v1
	v_add_u32_e32 v1, v0, v1
	v_and_b32_e32 v1, 0xfffffc00, v1
	v_sub_u32_e32 v0, v0, v1
	v_lshrrev_b32_e32 v1, 4, v0
	v_ashrrev_i32_e32 v3, 31, v9
	v_bitop3_b32 v0, v1, v0, 32 bitop3:0x6c
	v_lshrrev_b32_e32 v3, 26, v3
	v_ashrrev_i32_e32 v1, 31, v0
	v_add_u32_e32 v3, v9, v3
	s_add_u32 s36, s6, 0x5400000
	v_lshrrev_b32_e32 v1, 26, v1
	v_ashrrev_i32_e32 v13, 6, v3
	s_addc_u32 s37, s7, 0
	v_add_u32_e32 v1, v0, v1
	v_lshlrev_b32_e32 v3, 3, v13
	s_add_u32 s38, s6, 0x1a80000
	v_ashrrev_i32_e32 v12, 6, v1
	v_and_b32_e32 v3, -16, v3
	s_addc_u32 s39, s7, 0
	v_add_u32_e32 v3, v12, v3
	v_and_b32_e32 v4, 3, v12
	s_ashr_i32 s47, s14, 31
	v_and_or_b32 v4, v3, s8, v4
	s_lshr_b32 s8, s47, 29
	s_add_i32 s8, s14, s8
	s_ashr_i32 s12, s17, 6
	s_ashr_i32 s9, s8, 3
	s_and_b32 s8, s8, -8
	s_ashr_i32 s18, s17, 8
	s_lshl_b32 s46, s12, 10
	s_sub_i32 s8, s14, s8
	s_cmp_lt_i32 s8, 0
	s_movk_i32 s48, 0x211
	s_cselect_b32 s10, s48, 0x210
	s_mul_i32 s8, s8, s10
	s_add_i32 s8, s8, s9
	s_mul_hi_i32 s9, s8, 0x2e8ba2e9
	s_lshr_b32 s10, s9, 31
	s_ashr_i32 s9, s9, 5
	s_add_i32 s9, s9, s10
	s_lshl_b32 s10, s9, 3
	s_mulk_i32 s9, 0xb0
	s_sub_i32 s8, s8, s9
	s_sext_i32_i16 s9, s8
	s_bfe_u32 s9, s9, 0x3001c
	s_add_i32 s9, s8, s9
	s_sext_i32_i16 s11, s9
	s_and_b32 s9, s9, 0xfff8
	s_sub_i32 s8, s8, s9
	s_sext_i32_i16 s8, s8
	v_lshrrev_b32_e32 v5, 2, v3
	v_lshlrev_b32_e32 v6, 1, v3
	v_and_b32_e32 v1, 0xc0, v1
	s_lshr_b32 s16, s11, 3
	s_add_i32 s26, s10, s8
	v_and_b32_e32 v5, 4, v5
	v_and_b32_e32 v6, 24, v6
	v_sub_u32_e32 v0, v0, v1
	s_ashr_i32 s27, s26, 31
	s_bfe_i64 s[10:11], s[16:17], 0x100000
	v_or3_b32 v4, v4, v5, v6
	v_lshlrev_b32_e32 v5, 5, v13
	v_ashrrev_i16_sdwa v0, v2, sext(v0) dst_sel:DWORD dst_unused:UNUSED_PAD src0_sel:DWORD src1_sel:BYTE_0
	s_lshl_b64 s[8:9], s[26:27], 19
	s_lshl_b64 s[10:11], s[10:11], 19
	v_and_b32_e32 v5, 32, v5
	v_bfe_i32 v14, v0, 0, 16
	s_add_u32 s28, s38, s10
	v_add_lshl_u32 v0, v5, v14, 1
	s_addc_u32 s29, s39, s11
	s_add_i32 s27, s46, 0
	v_lshl_add_u32 v132, v4, 11, v0
	s_add_i32 m0, s27, 0x10000
	v_lshl_add_u32 v134, v3, 11, v0
	global_load_lds_dwordx4 v132, s[28:29]
	s_add_i32 m0, s27, 0x12000
	s_add_u32 s10, s28, 0x40000
	global_load_lds_dwordx4 v128, s[28:29]
	s_addc_u32 s11, s29, 0
	s_add_i32 m0, s27, 0x14000
	v_mov_b32_e32 v133, 0
	global_load_lds_dwordx4 v132, s[10:11]
	s_add_i32 m0, s27, 0x16000
	s_add_u32 s30, s36, s8
	s_addc_u32 s31, s37, s9
	s_add_i32 s49, s27, 0x2000
	global_load_lds_dwordx4 v128, s[10:11]
	s_mov_b32 m0, s27
	s_add_u32 s8, s30, 0x40000
	global_load_lds_dwordx4 v134, s[30:31]
	s_mov_b32 m0, s49
	s_addc_u32 s9, s31, 0
	s_add_i32 s52, s27, 0x4000
	global_load_lds_dwordx4 v130, s[30:31]
	s_mov_b32 m0, s52
	s_add_i32 s53, s27, 0x6000
	global_load_lds_dwordx4 v134, s[8:9]
	s_mov_b32 m0, s53
	v_mov_b32_e32 v129, v133
	global_load_lds_dwordx4 v130, s[8:9]
	v_mov_b32_e32 v135, v133
	v_mov_b32_e32 v131, v133
	s_cmp_eq_u32 s18, 1
	s_mov_b32 s54, 0
	v_lshl_add_u64 v[6:7], s[28:29], 0, v[132:133]
	v_lshl_add_u64 v[4:5], s[28:29], 0, v[128:129]
	v_lshl_add_u64 v[0:1], s[30:31], 0, v[134:135]
	s_cselect_b64 s[8:9], -1, 0
	s_cmp_lg_u32 s18, 1
	v_lshl_add_u64 v[2:3], s[30:31], 0, v[130:131]
	s_cbranch_scc1 .LBB0_697
	s_barrier

; #define PG8_STAGE(bufoff, gbase, voff) do { _Pragma("unroll") for (int _i = 0; _i < 2; ++_i) \
;         __builtin_amdgcn_global_load_lds((const unsigned*)((const char*)(gbase) + (voff)[_i]), (LAS unsigned*)(lds + (bufoff) + ldsw + _i * 8192), 16, 0, 0); } while (0)
; #define PG8_WAIT_V(n) asm volatile("s_waitcnt vmcnt(" #n ")" ::: "memory")
; #define PG8_BAR __builtin_amdgcn_s_barrier()
; template <class Epi>
; __device__ __forceinline__ void gemm_phase(LAS unsigned char* lds, const Gemm g, const StaticOrder& S, const Epi& E) {
;     ...
;     const int tid = tid_, wid = __builtin_amdgcn_readfirstlane(tid >> 6), lane = tid & 63, wr = wid >> 2, wc = wid & 3, fr = lane & 15, fq = lane >> 4;
;     const int K = g.K, nt = K / BK, lda = g.lda;
;     unsigned voffA[2], voffB[2];
; #pragma unroll
;     for (int i = 0; i < 2; ++i) { int R, C; stage_rc(tid * 16 + i * 8192, R, C); const int Rb = (R & ~31) + perm32(R & 31);
;         voffA[i] = (unsigned)(R * lda + C) * 2u; voffB[i] = (unsigned)(Rb * K + C) * 2u; }
;     const unsigned kstep = (unsigned)(BK * 2);
;     const unsigned hstepA = (unsigned)(HALF * lda * 2), hstepB = (unsigned)(HALF * K * 2);
;     const size_t tstepA = 2 * (size_t)hstepA, tstepB = 2 * (size_t)hstepB;
;     const unsigned ldsw = (unsigned)wid * 1024u;
;     const int aoff = lds_byte(wr * 64 + fr, fq * 8), boff = lds_byte(wc * 32 + fr, fq * 8);
;     ...
;     Unit cur, nxt; int ui = 0;
;     if (!S.next(0, cur)) return;
;     f32x4 acc[2][2][4][2];
; #pragma unroll
;     for (int a = 0; a < 2; ++a)
; #pragma unroll
;         for (int b = 0; b < 2; ++b)
; #pragma unroll
;             for (int m = 0; m < 4; ++m)
; #pragma unroll
;                 for (int n = 0; n < 2; ++n) acc[a][b][m][n] = (f32x4){0.f, 0.f, 0.f, 0.f};
;     bf16x8 At[4][2], B0[2][2], B1[2][2];
;     const char* cA = (const char*)g.A + (size_t)cur.pm * tstepA; const char* cB = (const char*)g.Bt + (size_t)cur.pn * tstepB;
;     PG8_STAGE(PG8_SB(0, 0), cB, voffB); PG8_STAGE(PG8_SB(0, 1), cB + hstepB, voffB); PG8_STAGE(PG8_SA(0, 0), cA, voffA); PG8_STAGE(PG8_SA(0, 1), cA + hstepA, voffA);
;     if (wr == 1) PG8_BAR;
;     PG8_WAIT_V(2); PG8_BAR;
;     PG8_STAGE(PG8_SB(1, 0), cB + kstep, voffB); PG8_STAGE(PG8_SA(1, 0), cA + kstep, voffA); PG8_STAGE(PG8_SB(1, 1), cB + hstepB + kstep, voffB);
;     PG8_WAIT_V(6); PG8_BAR;
.LBB0_867:
	s_or_b64 exec, exec, s[46:47]
	s_mov_b64 s[10:11], s[42:43]
	v_mov_b32_e32 v8, v154
	s_waitcnt lgkmcnt(0)
	s_barrier
	s_cselect_b32 s92, 1, 0
	s_cmp_lt_u32 s14, 128
	s_cbranch_scc1 .Lstg_1
	s_sleep 127
	s_sleep 127
	s_sleep 127
	s_sleep 127
	s_sleep 127
.Lstg_1:
	s_cmp_lg_u32 s92, 0
	s_and_b64 vcc, exec, s[2:3]
	v_readfirstlane_b32 s9, v8
	s_cbranch_vccnz .LBB0_883
	v_lshlrev_b32_e32 v0, 4, v8
	v_add_u32_e32 v1, 0x2000, v0
	v_ashrrev_i32_e32 v2, 31, v1
	v_lshrrev_b32_e32 v2, 22, v2
	v_add_u32_e32 v2, v1, v2
	v_ashrrev_i32_e32 v9, 10, v2
	v_mul_i32_i24_e32 v2, 0x400, v9
	v_sub_u32_e32 v1, v1, v2
	v_lshrrev_b32_e32 v2, 4, v1
	v_bitop3_b32 v1, v2, v1, 32 bitop3:0x6c
	v_ashrrev_i32_e32 v2, 31, v1
	v_lshrrev_b32_e32 v2, 26, v2
	v_add_u32_e32 v2, v1, v2
	v_lshlrev_b32_e32 v3, 3, v9
	v_ashrrev_i32_e32 v10, 6, v2
	v_and_b32_e32 v3, -16, v3
	v_add_u32_e32 v3, v10, v3
	v_and_b32_e32 v4, 3, v10
	s_mov_b32 s8, 0x1fffe0
	v_lshrrev_b32_e32 v5, 2, v3
	v_lshlrev_b32_e32 v6, 1, v3
	v_and_b32_e32 v2, 0xc0, v2
	v_and_or_b32 v4, v3, s8, v4
	v_and_b32_e32 v5, 4, v5
	v_and_b32_e32 v6, 24, v6
	v_sub_u32_e32 v1, v1, v2
	v_mov_b32_e32 v2, 1
	v_or3_b32 v4, v4, v5, v6
	v_lshlrev_b32_e32 v5, 5, v9
	v_ashrrev_i16_sdwa v1, v2, sext(v1) dst_sel:DWORD dst_unused:UNUSED_PAD src0_sel:DWORD src1_sel:BYTE_0
	v_and_b32_e32 v5, 32, v5
	v_bfe_i32 v11, v1, 0, 16
	v_add_lshl_u32 v1, v5, v11, 1
	v_lshl_add_u32 v128, v4, 11, v1
	v_lshl_add_u32 v130, v3, 11, v1
	v_bfe_i32 v1, v8, 27, 1
	v_lshrrev_b32_e32 v1, 22, v1
	v_add_u32_e32 v1, v0, v1
	v_and_b32_e32 v1, 0xfffffc00, v1
	v_sub_u32_e32 v0, v0, v1
	v_lshrrev_b32_e32 v1, 4, v0
	v_ashrrev_i32_e32 v3, 31, v8
	v_bitop3_b32 v0, v1, v0, 32 bitop3:0x6c
	v_lshrrev_b32_e32 v3, 26, v3
	v_ashrrev_i32_e32 v1, 31, v0
	v_add_u32_e32 v3, v8, v3
	s_add_u32 s40, s10, 0x5400000
	v_lshrrev_b32_e32 v1, 26, v1
	v_ashrrev_i32_e32 v13, 6, v3
	s_addc_u32 s41, s11, 0
	v_add_u32_e32 v1, v0, v1
	v_lshlrev_b32_e32 v3, 3, v13
	s_add_u32 s46, s10, 0x2b00000
	v_ashrrev_i32_e32 v12, 6, v1
	v_and_b32_e32 v3, -16, v3
	s_addc_u32 s47, s11, 0
	v_add_u32_e32 v3, v12, v3
	v_and_b32_e32 v4, 3, v12
	s_ashr_i32 s49, s14, 31
	v_and_or_b32 v4, v3, s8, v4
	s_lshr_b32 s8, s49, 29
	s_add_i32 s8, s14, s8
	s_ashr_i32 s15, s9, 6
	s_ashr_i32 s12, s8, 3
	s_and_b32 s8, s8, -8
	s_ashr_i32 s20, s9, 8
	s_lshl_b32 s48, s15, 10
	s_sub_i32 s8, s14, s8
	s_cmp_lt_i32 s8, 0
	s_movk_i32 s52, 0x211
	s_cselect_b32 s13, s52, 0x210
	s_mul_i32 s8, s8, s13
	s_add_i32 s8, s8, s12
	s_mul_hi_i32 s12, s8, 0x2e8ba2e9
	s_lshr_b32 s13, s12, 31
	s_ashr_i32 s12, s12, 5
	s_add_i32 s12, s12, s13
	s_lshl_b32 s13, s12, 3
	s_mulk_i32 s12, 0xb0
	s_sub_i32 s12, s8, s12
	s_sext_i32_i16 s8, s12
	s_bfe_u32 s8, s8, 0x3001c
	s_add_i32 s16, s12, s8
	s_sext_i32_i16 s8, s16
	s_and_b32 s16, s16, 0xfff8
	s_sub_i32 s12, s12, s16
	s_sext_i32_i16 s12, s12
	v_lshrrev_b32_e32 v5, 2, v3
	v_lshlrev_b32_e32 v6, 1, v3
	v_and_b32_e32 v1, 0xc0, v1
	s_lshr_b32 s8, s8, 3
	s_add_i32 s30, s13, s12
	v_and_b32_e32 v5, 4, v5
	v_and_b32_e32 v6, 24, v6
	v_sub_u32_e32 v0, v0, v1
	s_ashr_i32 s31, s30, 31
	s_bfe_i64 s[16:17], s[8:9], 0x100000
	v_or3_b32 v4, v4, v5, v6
	v_lshlrev_b32_e32 v5, 5, v13
	v_ashrrev_i16_sdwa v0, v2, sext(v0) dst_sel:DWORD dst_unused:UNUSED_PAD src0_sel:DWORD src1_sel:BYTE_0
	s_lshl_b64 s[12:13], s[30:31], 19
	s_lshl_b64 s[16:17], s[16:17], 19
	v_and_b32_e32 v5, 32, v5
	v_bfe_i32 v14, v0, 0, 16
	s_add_u32 s34, s46, s16
	v_add_lshl_u32 v0, v5, v14, 1
	s_addc_u32 s35, s47, s17
	s_add_i32 s31, s48, 0
	v_lshl_add_u32 v132, v4, 11, v0
	s_add_i32 m0, s31, 0x10000
	v_lshl_add_u32 v134, v3, 11, v0
	global_load_lds_dwordx4 v132, s[34:35]
	s_add_i32 m0, s31, 0x12000
	s_add_u32 s16, s34, 0x40000
	global_load_lds_dwordx4 v128, s[34:35]
	s_addc_u32 s17, s35, 0
	s_add_i32 m0, s31, 0x14000
	v_mov_b32_e32 v133, 0
	global_load_lds_dwordx4 v132, s[16:17]
	s_add_i32 m0, s31, 0x16000
	s_add_u32 s36, s40, s12
	s_addc_u32 s37, s41, s13
	s_add_i32 s53, s31, 0x2000
	global_load_lds_dwordx4 v128, s[16:17]
	s_mov_b32 m0, s31
	s_add_u32 s12, s36, 0x40000
	global_load_lds_dwordx4 v134, s[36:37]
	s_mov_b32 m0, s53
	s_addc_u32 s13, s37, 0
	s_add_i32 s54, s31, 0x4000
	global_load_lds_dwordx4 v130, s[36:37]
	s_mov_b32 m0, s54
	s_add_i32 s55, s31, 0x6000
	global_load_lds_dwordx4 v134, s[12:13]
	s_mov_b32 m0, s55
	v_mov_b32_e32 v129, v133
	global_load_lds_dwordx4 v130, s[12:13]
	v_mov_b32_e32 v135, v133
	v_mov_b32_e32 v131, v133
	s_cmp_eq_u32 s20, 1
	s_mov_b32 s56, 0
	v_lshl_add_u64 v[6:7], s[34:35], 0, v[132:133]
	v_lshl_add_u64 v[4:5], s[34:35], 0, v[128:129]
	v_lshl_add_u64 v[0:1], s[36:37], 0, v[134:135]
	s_cselect_b64 s[12:13], -1, 0
	s_cmp_lg_u32 s20, 1
	v_lshl_add_u64 v[2:3], s[36:37], 0, v[130:131]
	s_cbranch_scc1 .LBB0_870
	s_barrier

;     __device__ bool next(int i, Unit& u) const {
;         const long L = (long)i * G + c; if (L >= nwg) return false;
;         int wgid = (int)L; { const int q = nwg / NXCD, r = nwg % NXCD, xcd = wgid % NXCD, off = wgid / NXCD; wgid = (xcd < r ? xcd * (q + 1) : r * (q + 1) + (xcd - r) * q) + off; }
;         const int nig = WGM * nN, gid = wgid / nig, fm = gid * WGM, gsz = (nM - fm) < WGM ? (nM - fm) : WGM;
;         u.pm = fm + ((wgid % nig) % gsz); u.pn = (wgid % nig) / gsz; return true;
;     }
;     __device__ __forceinline__ void operator()(const f32x4 (&acc)[2][2][4][2], const Unit& u, int wr, int wc, int fr, int fq) const {
;     ...
;         for (int i = 0; i < 8; ++i) rsv[i] = (NP == 16) ? row_ss16_coop(ss, row0 + (i >> 2) * HALF + (i & 3) * 16, fq) : row_ss<1>(ss, row0 + (i >> 2) * HALF + (i & 3) * 16);
; #pragma unroll
;         for (int i = 0; i < 8; ++i) rsv[i] = __builtin_amdgcn_rsqf(rsv[i] * (1.0f / 1024.0f) + EPS);
.LBB0_873:
	v_lshl_add_u32 v244, s30, 8, v146
	v_ashrrev_i32_e32 v245, 31, v244
	v_lshl_add_u64 v[246:247], v[244:245], 2, s[10:11]
	global_load_dword v235, v[246:247], off
	global_load_dword v236, v[246:247], off offset:64
	global_load_dword v237, v[246:247], off offset:128
	global_load_dword v238, v[246:247], off offset:192
	global_load_dword v239, v[246:247], off offset:512
	global_load_dword v240, v[246:247], off offset:576
	global_load_dword v241, v[246:247], off offset:640
	global_load_dword v242, v[246:247], off offset:704
	s_add_i32 s56, s56, 1
	s_mul_i32 s8, s56, s59
	s_mul_hi_u32 s9, s56, s60
	s_add_i32 s9, s9, s8
	s_mul_i32 s8, s56, s60
	s_add_u32 s26, s8, s14
	s_addc_u32 s27, s9, s49
	v_cmp_gt_i64_e32 vcc, s[26:27], v[142:143]
	v_cmp_lt_i64_e64 s[8:9], s[26:27], v[140:141]
	s_cbranch_vccnz .LBB0_875
	s_ashr_i32 s22, s26, 31
	s_lshr_b32 s22, s22, 29
	s_add_i32 s22, s26, s22
	s_ashr_i32 s23, s22, 3
	s_and_b32 s22, s22, -8
	s_sub_i32 s22, s26, s22
	s_cmp_lt_i32 s22, 0
	s_cselect_b32 s24, s52, 0x210
	s_mul_i32 s22, s22, s24
	s_add_i32 s22, s22, s23
	s_mul_hi_i32 s23, s22, 0x2e8ba2e9
	s_lshr_b32 s24, s23, 31
	s_ashr_i32 s23, s23, 5
	s_add_i32 s23, s23, s24
	s_lshl_b32 s24, s23, 3
	s_sub_i32 s25, 0xc0, s24
	s_min_i32 s25, s25, 8
	s_abs_i32 s26, s25
	v_cvt_f32_u32_e32 v0, s26
	s_sub_i32 s28, 0, s26
	s_mulk_i32 s23, 0xb0
	s_sub_i32 s23, s22, s23
	v_rcp_iflag_f32_e32 v0, v0
	s_abs_i32 s22, s23
	s_xor_b32 s27, s23, s25
	s_ashr_i32 s27, s27, 31
	v_mul_f32_e32 v0, 0x4f7ffffe, v0
	v_cvt_u32_f32_e32 v0, v0
	s_nop 0
	v_readfirstlane_b32 s29, v0
	s_mul_i32 s28, s28, s29
	s_mul_hi_u32 s28, s29, s28
	s_add_i32 s29, s29, s28
	s_mul_hi_u32 s28, s22, s29
	s_mul_i32 s29, s28, s26
	s_sub_i32 s22, s22, s29
	s_add_i32 s38, s28, 1
	s_sub_i32 s29, s22, s26
	s_cmp_ge_u32 s22, s26
	s_cselect_b32 s28, s38, s28
	s_cselect_b32 s22, s29, s22
	s_add_i32 s29, s28, 1
	s_cmp_ge_u32 s22, s26
	s_cselect_b32 s22, s29, s28
	s_xor_b32 s22, s22, s27
	s_sub_i32 s22, s22, s27
	s_mul_i32 s25, s22, s25
	s_sub_i32 s23, s23, s25
	s_add_i32 s24, s24, s23

; #define GAS __attribute__((address_space(1)))
; __device__ __forceinline__ unsigned cvt_pk_bf16(float lo, float hi) { f32x2_t v = {lo, hi}; bf16x2_t b = __builtin_convertvector(v, bf16x2_t); return __builtin_bit_cast(unsigned, b); }
;     __device__ __forceinline__ void operator()(const f32x4 (&acc)[2][2][4][2], const Unit& u, int wr, int wc, int fr, int fq) const {
;         const int row0 = u.pm * BM + wr * 64 + fr, col0 = u.pn * 128 + wc * 32 + 8 * fq;
;         float rsv[8];
; #pragma unroll
;         for (int i = 0; i < 8; ++i) rsv[i] = (NP == 16) ? row_ss16_coop(ss, row0 + (i >> 2) * HALF + (i & 3) * 16, fq) : row_ss<1>(ss, row0 + (i >> 2) * HALF + (i & 3) * 16);
; #pragma unroll
;         for (int i = 0; i < 8; ++i) rsv[i] = __builtin_amdgcn_rsqf(rsv[i] * (1.0f / 1024.0f) + EPS);
; #pragma unroll
;         for (int ai = 0; ai < 2; ++ai)
; #pragma unroll
;             for (int m = 0; m < 4; ++m) {
;                 const int row = row0 + ai * HALF + m * 16;
;                 const float rs = rsv[ai * 4 + m], c1 = -rs * LOG2E, rs2 = rs * rs;
;                 float h[8];
; #pragma unroll
;                 for (int n = 0; n < 2; ++n)
; #pragma unroll
;                     for (int i = 0; i < 4; ++i) {
;                         const float g = acc[ai][0][m][n][i], uu = acc[ai][1][m][n][i];
;                         const float e = __builtin_amdgcn_exp2f(g * c1);
;                         h[n * 4 + i] = (g * uu) * (rs2 * __builtin_amdgcn_rcpf(1.0f + e));
;                     }
;                 u32x4 w; w.x = cvt_pk_bf16(h[0], h[1]); w.y = cvt_pk_bf16(h[2], h[3]); w.z = cvt_pk_bf16(h[4], h[5]); w.w = cvt_pk_bf16(h[6], h[7]);
;                 *(GAS u32x4*)(H + (size_t)row * FF + col0) = w;
;                 asm volatile("" ::: "memory");
;             }
.LBB0_879:
	v_lshl_add_u32 v144, s30, 8, v146
	v_mov_b32_e32 v145, v235
	v_mov_b32_e32 v164, v236
	v_mov_b32_e32 v165, v237
	v_mov_b32_e32 v166, v238
	v_mov_b32_e32 v167, v239
	v_mov_b32_e32 v168, v240
	v_mov_b32_e32 v169, v241
	v_mov_b32_e32 v170, v242
	v_lshl_or_b32 v156, s15, 7, v148
	v_pk_mul_f32 v[160:161], v[112:113], v[120:121]
	v_mov_b64_e32 v[120:121], s[16:17]
	v_ashrrev_i32_e32 v157, 31, v156
	v_pk_mul_f32 v[158:159], v[114:115], v[122:123]
	v_pk_mul_f32 v[162:163], v[110:111], v[106:107]
	v_mad_i64_i32 v[122:123], s[34:35], v144, s63, v[120:121]
	v_lshlrev_b64 v[106:107], 1, v[156:157]
	v_lshl_add_u64 v[156:157], v[122:123], 0, v[106:107]
	v_pk_mul_f32 v[126:127], v[118:119], v[126:127]
	v_pk_mul_f32 v[124:125], v[116:117], v[124:125]
	v_pk_mul_f32 v[98:99], v[102:103], v[98:99]
	v_pk_mul_f32 v[104:105], v[108:109], v[104:105]
	v_pk_mul_f32 v[96:97], v[100:101], v[96:97]
	v_pk_mul_f32 v[90:91], v[94:95], v[90:91]
	v_pk_mul_f32 v[88:89], v[92:93], v[88:89]
	v_pk_mul_f32 v[82:83], v[86:87], v[82:83]
	v_pk_mul_f32 v[80:81], v[84:85], v[80:81]
	v_pk_mul_f32 v[74:75], v[78:79], v[74:75]
	v_pk_mul_f32 v[72:73], v[76:77], v[72:73]
	v_pk_mul_f32 v[66:67], v[70:71], v[66:67]
	v_pk_mul_f32 v[64:65], v[68:69], v[64:65]
	v_pk_mul_f32 v[58:59], v[62:63], v[58:59]
	v_pk_mul_f32 v[56:57], v[60:61], v[56:57]
	v_pk_mul_f32 v[50:51], v[54:55], v[50:51]
	v_pk_mul_f32 v[48:49], v[52:53], v[48:49]
	v_add_u32_e32 v171, 0x80, v144
	v_pk_mul_f32 v[42:43], v[46:47], v[42:43]
	v_pk_mul_f32 v[40:41], v[44:45], v[40:41]
	v_pk_mul_f32 v[34:35], v[38:39], v[34:35]
	v_pk_mul_f32 v[32:33], v[36:37], v[32:33]
	v_pk_mul_f32 v[26:27], v[30:31], v[26:27]
	v_pk_mul_f32 v[24:25], v[28:29], v[24:25]
	v_pk_mul_f32 v[18:19], v[22:23], v[18:19]
	v_pk_mul_f32 v[16:17], v[20:21], v[16:17]
	v_pk_mul_f32 v[10:11], v[14:15], v[10:11]
	v_pk_mul_f32 v[8:9], v[12:13], v[8:9]
	v_pk_mul_f32 v[2:3], v[6:7], v[2:3]
	v_pk_mul_f32 v[0:1], v[4:5], v[0:1]
	s_andn2_b64 vcc, exec, s[8:9]
	s_mov_b64 s[8:9], -1
	s_waitcnt lgkmcnt(0)
	v_fmamk_f32 v122, v145, 0x3a800000, v153
	v_fmamk_f32 v123, v164, 0x3a800000, v153
	v_fmamk_f32 v145, v165, 0x3a800000, v153
	v_fmamk_f32 v164, v166, 0x3a800000, v153
	v_fmamk_f32 v165, v167, 0x3a800000, v153
	v_fmamk_f32 v166, v168, 0x3a800000, v153
	v_fmamk_f32 v167, v169, 0x3a800000, v153
	v_rsq_f32_e32 v169, v122
	v_fmamk_f32 v168, v170, 0x3a800000, v153
	v_rsq_f32_e32 v170, v123
	v_rsq_f32_e32 v123, v167
	v_mul_f32_e32 v167, 0xbfb8aa3b, v169
	v_mul_f32_e32 v116, v116, v167
	v_mul_f32_e32 v174, 0xbfb8aa3b, v170
	v_mul_f32_e32 v117, v117, v167
	v_mul_f32_e32 v118, v118, v167
	v_mul_f32_e32 v119, v119, v167
	v_mul_f32_e32 v112, v112, v167
	v_mul_f32_e32 v113, v113, v167
	v_mul_f32_e32 v114, v114, v167
	v_mul_f32_e32 v115, v115, v167
	v_mul_f32_e32 v110, v110, v174
	v_exp_f32_e32 v116, v116
	v_exp_f32_e32 v117, v117
	v_exp_f32_e32 v118, v118
	v_exp_f32_e32 v119, v119
	v_exp_f32_e32 v112, v112
	v_exp_f32_e32 v113, v113
	v_exp_f32_e32 v114, v114
	v_exp_f32_e32 v115, v115
	v_exp_f32_e32 v110, v110
	v_mul_f32_e32 v111, v111, v174
	v_rsq_f32_e32 v172, v164
	v_rsq_f32_e32 v173, v166
	v_mul_f32_e32 v164, v169, v169
	v_mul_f32_e32 v166, v170, v170
	v_exp_f32_e32 v169, v111
	v_add_f32_e32 v111, 1.0, v116
	v_add_f32_e32 v116, 1.0, v117
	v_add_f32_e32 v117, 1.0, v118
	v_add_f32_e32 v118, 1.0, v119
	v_add_f32_e32 v119, 1.0, v112
	v_add_f32_e32 v170, 1.0, v113
	v_add_f32_e32 v175, 1.0, v114
	v_add_f32_e32 v176, 1.0, v115
	v_rsq_f32_e32 v165, v165
	v_add_f32_e32 v177, 1.0, v110
	v_rcp_f32_e32 v110, v111
	v_rcp_f32_e32 v111, v116
	v_rcp_f32_e32 v112, v117
	v_rcp_f32_e32 v113, v118
	v_rcp_f32_e32 v114, v119
	v_rcp_f32_e32 v115, v170
	v_rcp_f32_e32 v116, v175
	v_rcp_f32_e32 v117, v176
	v_pk_mul_f32 v[110:111], v[164:165], v[110:111] op_sel_hi:[0,1]
	v_pk_mul_f32 v[112:113], v[164:165], v[112:113] op_sel_hi:[0,1]
	v_pk_mul_f32 v[114:115], v[164:165], v[114:115] op_sel_hi:[0,1]
	v_pk_mul_f32 v[116:117], v[164:165], v[116:117] op_sel_hi:[0,1]
	v_pk_mul_f32 v[110:111], v[124:125], v[110:111]
	v_pk_mul_f32 v[112:113], v[126:127], v[112:113]
	v_pk_mul_f32 v[114:115], v[160:161], v[114:115]
	v_pk_mul_f32 v[116:117], v[158:159], v[116:117]
	v_cvt_pk_bf16_f32 v110, v110, v111
	v_cvt_pk_bf16_f32 v111, v112, v113
	v_cvt_pk_bf16_f32 v112, v114, v115
	v_cvt_pk_bf16_f32 v113, v116, v117
	global_store_dwordx4 v[156:157], v[110:113], off
	v_rsq_f32_e32 v122, v168
	v_mul_f32_e32 v167, v108, v174
	v_add_f32_e32 v110, 1.0, v169
	v_mul_f32_e32 v168, v109, v174
	v_rcp_f32_e32 v169, v110
	v_mul_f32_e32 v110, v100, v174
	v_mul_f32_e32 v111, v101, v174
	v_exp_f32_e32 v167, v167
	v_exp_f32_e32 v168, v168
	v_exp_f32_e32 v110, v110
	v_exp_f32_e32 v111, v111
	v_mul_f32_e32 v112, v102, v174
	v_mul_f32_e32 v113, v103, v174
	v_exp_f32_e32 v112, v112
	v_exp_f32_e32 v113, v113
	v_add_f32_e32 v167, 1.0, v167
	v_add_f32_e32 v168, 1.0, v168
	v_add_f32_e32 v110, 1.0, v110
	v_add_f32_e32 v111, 1.0, v111
	v_rcp_f32_e32 v118, v167
	v_rcp_f32_e32 v119, v168
	v_rcp_f32_e32 v110, v110
	v_rcp_f32_e32 v111, v111
	v_add_f32_e32 v102, 1.0, v112
	v_add_f32_e32 v103, 1.0, v113
	v_rcp_f32_e32 v168, v177
	v_rcp_f32_e32 v102, v102
	v_rcp_f32_e32 v103, v103
	v_rsq_f32_e32 v145, v145
	v_pk_mul_f32 v[108:109], v[166:167], v[118:119] op_sel_hi:[0,1]
	v_pk_mul_f32 v[100:101], v[166:167], v[110:111] op_sel_hi:[0,1]
	v_pk_mul_f32 v[104:105], v[104:105], v[108:109]
	v_pk_mul_f32 v[108:109], v[166:167], v[168:169] op_sel_hi:[0,1]
	v_pk_mul_f32 v[100:101], v[96:97], v[100:101]
	v_pk_mul_f32 v[96:97], v[166:167], v[102:103] op_sel_hi:[0,1]
	v_or_b32_e32 v110, 16, v144
	v_pk_mul_f32 v[108:109], v[162:163], v[108:109]
; #define GAS __attribute__((address_space(1)))
; __device__ __forceinline__ unsigned cvt_pk_bf16(float lo, float hi) { f32x2_t v = {lo, hi}; bf16x2_t b = __builtin_convertvector(v, bf16x2_t); return __builtin_bit_cast(unsigned, b); }
;     __device__ __forceinline__ void operator()(const f32x4 (&acc)[2][2][4][2], const Unit& u, int wr, int wc, int fr, int fq) const {
;     ...
;         for (int ai = 0; ai < 2; ++ai)
; #pragma unroll
;             for (int m = 0; m < 4; ++m) {
;                 const int row = row0 + ai * HALF + m * 16;
;                 const float rs = rsv[ai * 4 + m], c1 = -rs * LOG2E, rs2 = rs * rs;
;                 float h[8];
; #pragma unroll
;                 for (int n = 0; n < 2; ++n)
; #pragma unroll
;                     for (int i = 0; i < 4; ++i) {
;                         const float g = acc[ai][0][m][n][i], uu = acc[ai][1][m][n][i];
;                         const float e = __builtin_amdgcn_exp2f(g * c1);
;                         h[n * 4 + i] = (g * uu) * (rs2 * __builtin_amdgcn_rcpf(1.0f + e));
;                     }
;                 u32x4 w; w.x = cvt_pk_bf16(h[0], h[1]); w.y = cvt_pk_bf16(h[2], h[3]); w.z = cvt_pk_bf16(h[4], h[5]); w.w = cvt_pk_bf16(h[6], h[7]);
;                 *(GAS u32x4*)(H + (size_t)row * FF + col0) = w;
;                 asm volatile("" ::: "memory");
;             }
	v_pk_mul_f32 v[102:103], v[98:99], v[96:97]
	v_cvt_pk_bf16_f32 v98, v100, v101
	v_mad_i64_i32 v[100:101], s[34:35], v110, s63, v[120:121]
	v_cvt_pk_bf16_f32 v96, v104, v105
	v_cvt_pk_bf16_f32 v97, v108, v109
	v_cvt_pk_bf16_f32 v99, v102, v103
	v_lshl_add_u64 v[100:101], v[100:101], 0, v[106:107]
	global_store_dwordx4 v[100:101], v[96:99], off
	s_nop 1
	v_mul_f32_e32 v97, 0xbfb8aa3b, v145
	v_mul_f32_e32 v96, v92, v97
	v_exp_f32_e32 v98, v96
	v_mul_f32_e32 v96, v93, v97
	v_exp_f32_e32 v99, v96
	v_mul_f32_e32 v100, v94, v97
	v_mul_f32_e32 v101, v95, v97
	v_exp_f32_e32 v100, v100
	v_exp_f32_e32 v101, v101
	v_add_f32_e32 v98, 1.0, v98
	v_add_f32_e32 v99, 1.0, v99
	v_rcp_f32_e32 v98, v98
	v_rcp_f32_e32 v99, v99
	v_add_f32_e32 v94, 1.0, v100
	v_add_f32_e32 v95, 1.0, v101
	v_rcp_f32_e32 v94, v94
	v_rcp_f32_e32 v95, v95
	v_mul_f32_e32 v96, v145, v145
	v_pk_mul_f32 v[92:93], v[96:97], v[98:99] op_sel_hi:[0,1]
	v_pk_mul_f32 v[88:89], v[88:89], v[92:93]
	v_pk_mul_f32 v[92:93], v[96:97], v[94:95] op_sel_hi:[0,1]
	v_mul_f32_e32 v94, v84, v97
	v_mul_f32_e32 v95, v85, v97
	v_exp_f32_e32 v94, v94
	v_exp_f32_e32 v95, v95
	v_pk_mul_f32 v[90:91], v[90:91], v[92:93]
	v_add_f32_e32 v92, 1.0, v94
	v_add_f32_e32 v93, 1.0, v95
	v_mul_f32_e32 v94, v86, v97
	v_mul_f32_e32 v95, v87, v97
	v_exp_f32_e32 v94, v94
	v_exp_f32_e32 v95, v95
	v_rcp_f32_e32 v92, v92
	v_rcp_f32_e32 v93, v93
	v_add_f32_e32 v86, 1.0, v94
	v_add_f32_e32 v87, 1.0, v95
	v_rcp_f32_e32 v86, v86
	v_rcp_f32_e32 v87, v87
	v_pk_mul_f32 v[84:85], v[96:97], v[92:93] op_sel_hi:[0,1]
	v_pk_mul_f32 v[84:85], v[80:81], v[84:85]
	v_or_b32_e32 v92, 32, v144
	v_pk_mul_f32 v[80:81], v[96:97], v[86:87] op_sel_hi:[0,1]
	v_pk_mul_f32 v[86:87], v[82:83], v[80:81]
	v_cvt_pk_bf16_f32 v82, v84, v85
	v_mad_i64_i32 v[84:85], s[34:35], v92, s63, v[120:121]
	v_cvt_pk_bf16_f32 v80, v88, v89
	v_cvt_pk_bf16_f32 v81, v90, v91
	v_cvt_pk_bf16_f32 v83, v86, v87
	v_lshl_add_u64 v[84:85], v[84:85], 0, v[106:107]
	global_store_dwordx4 v[84:85], v[80:83], off
	s_nop 1
	v_mul_f32_e32 v81, 0xbfb8aa3b, v172
	v_mul_f32_e32 v80, v76, v81
	v_exp_f32_e32 v82, v80
	v_mul_f32_e32 v80, v77, v81
	v_exp_f32_e32 v83, v80
	v_mul_f32_e32 v84, v78, v81
	v_mul_f32_e32 v85, v79, v81
	v_exp_f32_e32 v84, v84
	v_exp_f32_e32 v85, v85
	v_add_f32_e32 v82, 1.0, v82
	v_add_f32_e32 v83, 1.0, v83
	v_rcp_f32_e32 v82, v82
	v_rcp_f32_e32 v83, v83
	v_add_f32_e32 v78, 1.0, v84
	v_add_f32_e32 v79, 1.0, v85
	v_rcp_f32_e32 v78, v78
	v_rcp_f32_e32 v79, v79
	v_mul_f32_e32 v80, v172, v172
	v_pk_mul_f32 v[76:77], v[80:81], v[82:83] op_sel_hi:[0,1]
	v_pk_mul_f32 v[72:73], v[72:73], v[76:77]
	v_pk_mul_f32 v[76:77], v[80:81], v[78:79] op_sel_hi:[0,1]
	v_mul_f32_e32 v78, v68, v81
	v_mul_f32_e32 v79, v69, v81
	v_exp_f32_e32 v78, v78
	v_exp_f32_e32 v79, v79
	v_pk_mul_f32 v[74:75], v[74:75], v[76:77]
	v_add_f32_e32 v76, 1.0, v78
	v_add_f32_e32 v77, 1.0, v79
	v_mul_f32_e32 v78, v70, v81
	v_mul_f32_e32 v79, v71, v81
	v_exp_f32_e32 v78, v78
	v_exp_f32_e32 v79, v79
	v_rcp_f32_e32 v76, v76
	v_rcp_f32_e32 v77, v77
	v_add_f32_e32 v70, 1.0, v78
	v_add_f32_e32 v71, 1.0, v79
	v_rcp_f32_e32 v70, v70
	v_rcp_f32_e32 v71, v71
	v_pk_mul_f32 v[68:69], v[80:81], v[76:77] op_sel_hi:[0,1]
	v_pk_mul_f32 v[68:69], v[64:65], v[68:69]
	v_or_b32_e32 v76, 48, v144
	v_pk_mul_f32 v[64:65], v[80:81], v[70:71] op_sel_hi:[0,1]
	v_pk_mul_f32 v[70:71], v[66:67], v[64:65]
	v_cvt_pk_bf16_f32 v66, v68, v69
	v_mad_i64_i32 v[68:69], s[34:35], v76, s63, v[120:121]
	v_cvt_pk_bf16_f32 v64, v72, v73
	v_cvt_pk_bf16_f32 v65, v74, v75
	v_cvt_pk_bf16_f32 v67, v70, v71
	v_lshl_add_u64 v[68:69], v[68:69], 0, v[106:107]
	global_store_dwordx4 v[68:69], v[64:67], off
	s_nop 1
	v_mul_f32_e32 v65, 0xbfb8aa3b, v165
	v_mul_f32_e32 v64, v60, v65
	v_exp_f32_e32 v66, v64
	v_mul_f32_e32 v64, v61, v65
	v_exp_f32_e32 v67, v64
	v_mul_f32_e32 v68, v62, v65
	v_mul_f32_e32 v69, v63, v65
	v_exp_f32_e32 v68, v68
	v_exp_f32_e32 v69, v69
	v_add_f32_e32 v66, 1.0, v66
	v_add_f32_e32 v67, 1.0, v67
	v_rcp_f32_e32 v66, v66
	v_rcp_f32_e32 v67, v67
	v_add_f32_e32 v62, 1.0, v68
	v_add_f32_e32 v63, 1.0, v69
	v_rcp_f32_e32 v62, v62
	v_rcp_f32_e32 v63, v63
	v_mul_f32_e32 v64, v165, v165
	v_pk_mul_f32 v[60:61], v[64:65], v[66:67] op_sel_hi:[0,1]
	v_pk_mul_f32 v[56:57], v[56:57], v[60:61]
	v_pk_mul_f32 v[60:61], v[64:65], v[62:63] op_sel_hi:[0,1]
	v_mul_f32_e32 v62, v52, v65
	v_mul_f32_e32 v63, v53, v65
	v_exp_f32_e32 v62, v62
	v_exp_f32_e32 v63, v63
	v_pk_mul_f32 v[58:59], v[58:59], v[60:61]
	v_add_f32_e32 v60, 1.0, v62
	v_add_f32_e32 v61, 1.0, v63
	v_mul_f32_e32 v62, v54, v65
	v_mul_f32_e32 v63, v55, v65
	v_exp_f32_e32 v62, v62
	v_exp_f32_e32 v63, v63
	v_rcp_f32_e32 v60, v60
	v_rcp_f32_e32 v61, v61
	v_add_f32_e32 v54, 1.0, v62
	v_add_f32_e32 v55, 1.0, v63
	v_rcp_f32_e32 v54, v54
	v_rcp_f32_e32 v55, v55
	v_pk_mul_f32 v[52:53], v[64:65], v[60:61] op_sel_hi:[0,1]
	v_pk_mul_f32 v[52:53], v[48:49], v[52:53]
	v_pk_mul_f32 v[48:49], v[64:65], v[54:55] op_sel_hi:[0,1]
	v_pk_mul_f32 v[54:55], v[50:51], v[48:49]
	v_cvt_pk_bf16_f32 v50, v52, v53
	v_mad_i64_i32 v[52:53], s[34:35], v171, s63, v[120:121]
	v_cvt_pk_bf16_f32 v48, v56, v57
	v_cvt_pk_bf16_f32 v49, v58, v59
; #define GAS __attribute__((address_space(1)))
; __device__ __forceinline__ unsigned cvt_pk_bf16(float lo, float hi) { f32x2_t v = {lo, hi}; bf16x2_t b = __builtin_convertvector(v, bf16x2_t); return __builtin_bit_cast(unsigned, b); }
; #define PG8_BAR __builtin_amdgcn_s_barrier()
;     __device__ __forceinline__ void operator()(const f32x4 (&acc)[2][2][4][2], const Unit& u, int wr, int wc, int fr, int fq) const {
;     ...
;         for (int ai = 0; ai < 2; ++ai)
; #pragma unroll
;             for (int m = 0; m < 4; ++m) {
;                 const int row = row0 + ai * HALF + m * 16;
;                 const float rs = rsv[ai * 4 + m], c1 = -rs * LOG2E, rs2 = rs * rs;
;                 float h[8];
; #pragma unroll
;                 for (int n = 0; n < 2; ++n)
; #pragma unroll
;                     for (int i = 0; i < 4; ++i) {
;                         const float g = acc[ai][0][m][n][i], uu = acc[ai][1][m][n][i];
;                         const float e = __builtin_amdgcn_exp2f(g * c1);
;                         h[n * 4 + i] = (g * uu) * (rs2 * __builtin_amdgcn_rcpf(1.0f + e));
;                     }
;                 u32x4 w; w.x = cvt_pk_bf16(h[0], h[1]); w.y = cvt_pk_bf16(h[2], h[3]); w.z = cvt_pk_bf16(h[4], h[5]); w.w = cvt_pk_bf16(h[6], h[7]);
;                 *(GAS u32x4*)(H + (size_t)row * FF + col0) = w;
;                 asm volatile("" ::: "memory");
;             }
; template <class Epi>
; __device__ __forceinline__ void gemm_phase(LAS unsigned char* lds, const Gemm g, const StaticOrder& S, const Epi& E) {
;     ...
;         if (wr == 0) PG8_BAR;
;         E(acc, cur, wr, wc, fr, fq);
;         if (!has_next) break;
; #pragma unroll
;         for (int a = 0; a < 2; ++a)
; #pragma unroll
;             for (int b = 0; b < 2; ++b)
; #pragma unroll
;                 for (int m = 0; m < 4; ++m)
; #pragma unroll
;                     for (int n = 0; n < 2; ++n) acc[a][b][m][n] = (f32x4){0.f, 0.f, 0.f, 0.f};
;         cur = nxt; cA = nA; cB = nB; ++ui;
;         if (wr == 1) PG8_BAR;
	v_cvt_pk_bf16_f32 v51, v54, v55
	v_lshl_add_u64 v[52:53], v[52:53], 0, v[106:107]
	global_store_dwordx4 v[52:53], v[48:51], off
	s_nop 1
	v_mul_f32_e32 v49, 0xbfb8aa3b, v173
	v_mul_f32_e32 v48, v44, v49
	v_exp_f32_e32 v50, v48
	v_mul_f32_e32 v48, v45, v49
	v_exp_f32_e32 v51, v48
	v_mul_f32_e32 v52, v46, v49
	v_mul_f32_e32 v53, v47, v49
	v_exp_f32_e32 v52, v52
	v_exp_f32_e32 v53, v53
	v_add_f32_e32 v50, 1.0, v50
	v_add_f32_e32 v51, 1.0, v51
	v_rcp_f32_e32 v50, v50
	v_rcp_f32_e32 v51, v51
	v_add_f32_e32 v46, 1.0, v52
	v_add_f32_e32 v47, 1.0, v53
	v_rcp_f32_e32 v46, v46
	v_rcp_f32_e32 v47, v47
	v_mul_f32_e32 v48, v173, v173
	v_pk_mul_f32 v[44:45], v[48:49], v[50:51] op_sel_hi:[0,1]
	v_pk_mul_f32 v[40:41], v[40:41], v[44:45]
	v_pk_mul_f32 v[44:45], v[48:49], v[46:47] op_sel_hi:[0,1]
	v_mul_f32_e32 v46, v36, v49
	v_mul_f32_e32 v47, v37, v49
	v_exp_f32_e32 v46, v46
	v_exp_f32_e32 v47, v47
	v_pk_mul_f32 v[42:43], v[42:43], v[44:45]
	v_add_f32_e32 v44, 1.0, v46
	v_add_f32_e32 v45, 1.0, v47
	v_mul_f32_e32 v46, v38, v49
	v_mul_f32_e32 v47, v39, v49
	v_exp_f32_e32 v46, v46
	v_exp_f32_e32 v47, v47
	v_rcp_f32_e32 v44, v44
	v_rcp_f32_e32 v45, v45
	v_add_f32_e32 v38, 1.0, v46
	v_add_f32_e32 v39, 1.0, v47
	v_rcp_f32_e32 v38, v38
	v_rcp_f32_e32 v39, v39
	v_pk_mul_f32 v[36:37], v[48:49], v[44:45] op_sel_hi:[0,1]
	v_pk_mul_f32 v[36:37], v[32:33], v[36:37]
	v_add_u32_e32 v44, 0x90, v144
	v_pk_mul_f32 v[32:33], v[48:49], v[38:39] op_sel_hi:[0,1]
	v_pk_mul_f32 v[38:39], v[34:35], v[32:33]
	v_cvt_pk_bf16_f32 v34, v36, v37
	v_mad_i64_i32 v[36:37], s[34:35], v44, s63, v[120:121]
	v_cvt_pk_bf16_f32 v32, v40, v41
	v_cvt_pk_bf16_f32 v33, v42, v43
	v_cvt_pk_bf16_f32 v35, v38, v39
	v_lshl_add_u64 v[36:37], v[36:37], 0, v[106:107]
	global_store_dwordx4 v[36:37], v[32:35], off
	s_nop 1
	v_mul_f32_e32 v33, 0xbfb8aa3b, v123
	v_mul_f32_e32 v32, v28, v33
	v_exp_f32_e32 v34, v32
	v_mul_f32_e32 v32, v29, v33
	v_exp_f32_e32 v35, v32
	v_mul_f32_e32 v36, v30, v33
	v_mul_f32_e32 v37, v31, v33
	v_exp_f32_e32 v36, v36
	v_exp_f32_e32 v37, v37
	v_add_f32_e32 v34, 1.0, v34
	v_add_f32_e32 v35, 1.0, v35
	v_rcp_f32_e32 v34, v34
	v_rcp_f32_e32 v35, v35
	v_add_f32_e32 v30, 1.0, v36
	v_add_f32_e32 v31, 1.0, v37
	v_rcp_f32_e32 v30, v30
	v_rcp_f32_e32 v31, v31
	v_mul_f32_e32 v32, v123, v123
	v_pk_mul_f32 v[28:29], v[32:33], v[34:35] op_sel_hi:[0,1]
	v_pk_mul_f32 v[24:25], v[24:25], v[28:29]
	v_pk_mul_f32 v[28:29], v[32:33], v[30:31] op_sel_hi:[0,1]
	v_mul_f32_e32 v30, v20, v33
	v_mul_f32_e32 v31, v21, v33
	v_exp_f32_e32 v30, v30
	v_exp_f32_e32 v31, v31
	v_pk_mul_f32 v[26:27], v[26:27], v[28:29]
	v_add_f32_e32 v28, 1.0, v30
	v_add_f32_e32 v29, 1.0, v31
	v_mul_f32_e32 v30, v22, v33
	v_mul_f32_e32 v31, v23, v33
	v_exp_f32_e32 v30, v30
	v_exp_f32_e32 v31, v31
	v_rcp_f32_e32 v28, v28
	v_rcp_f32_e32 v29, v29
	v_add_f32_e32 v22, 1.0, v30
	v_add_f32_e32 v23, 1.0, v31
	v_rcp_f32_e32 v22, v22
	v_rcp_f32_e32 v23, v23
	v_pk_mul_f32 v[20:21], v[32:33], v[28:29] op_sel_hi:[0,1]
	v_pk_mul_f32 v[20:21], v[16:17], v[20:21]
	v_add_u32_e32 v28, 0xa0, v144
	v_pk_mul_f32 v[16:17], v[32:33], v[22:23] op_sel_hi:[0,1]
	v_pk_mul_f32 v[22:23], v[18:19], v[16:17]
	v_cvt_pk_bf16_f32 v18, v20, v21
	v_mad_i64_i32 v[20:21], s[34:35], v28, s63, v[120:121]
	v_cvt_pk_bf16_f32 v16, v24, v25
	v_cvt_pk_bf16_f32 v17, v26, v27
	v_cvt_pk_bf16_f32 v19, v22, v23
	v_lshl_add_u64 v[20:21], v[20:21], 0, v[106:107]
	global_store_dwordx4 v[20:21], v[16:19], off
	s_nop 1
	v_mul_f32_e32 v17, 0xbfb8aa3b, v122
	v_mul_f32_e32 v16, v12, v17
	v_exp_f32_e32 v18, v16
	v_mul_f32_e32 v16, v13, v17
	v_exp_f32_e32 v19, v16
	v_mul_f32_e32 v20, v14, v17
	v_mul_f32_e32 v21, v15, v17
	v_exp_f32_e32 v20, v20
	v_exp_f32_e32 v21, v21
	v_add_f32_e32 v18, 1.0, v18
	v_add_f32_e32 v19, 1.0, v19
	v_rcp_f32_e32 v18, v18
	v_rcp_f32_e32 v19, v19
	v_add_f32_e32 v14, 1.0, v20
	v_add_f32_e32 v15, 1.0, v21
	v_rcp_f32_e32 v14, v14
	v_rcp_f32_e32 v15, v15
	v_mul_f32_e32 v16, v122, v122
	v_pk_mul_f32 v[12:13], v[16:17], v[18:19] op_sel_hi:[0,1]
	v_pk_mul_f32 v[8:9], v[8:9], v[12:13]
	v_pk_mul_f32 v[12:13], v[16:17], v[14:15] op_sel_hi:[0,1]
	v_mul_f32_e32 v14, v4, v17
	v_mul_f32_e32 v15, v5, v17
	v_exp_f32_e32 v14, v14
	v_exp_f32_e32 v15, v15
	v_pk_mul_f32 v[10:11], v[10:11], v[12:13]
	v_add_f32_e32 v12, 1.0, v14
	v_add_f32_e32 v13, 1.0, v15
	v_mul_f32_e32 v14, v6, v17
	v_mul_f32_e32 v15, v7, v17
	v_exp_f32_e32 v14, v14
	v_exp_f32_e32 v15, v15
	v_rcp_f32_e32 v12, v12
	v_rcp_f32_e32 v13, v13
	v_add_f32_e32 v6, 1.0, v14
	v_add_f32_e32 v7, 1.0, v15
	v_rcp_f32_e32 v6, v6
	v_rcp_f32_e32 v7, v7
	v_pk_mul_f32 v[4:5], v[16:17], v[12:13] op_sel_hi:[0,1]
	v_pk_mul_f32 v[4:5], v[0:1], v[4:5]
	v_add_u32_e32 v12, 0xb0, v144
	v_pk_mul_f32 v[0:1], v[16:17], v[6:7] op_sel_hi:[0,1]
	v_pk_mul_f32 v[6:7], v[2:3], v[0:1]
	v_cvt_pk_bf16_f32 v2, v4, v5
	v_mad_i64_i32 v[4:5], s[34:35], v12, s63, v[120:121]
	v_cvt_pk_bf16_f32 v0, v8, v9
	v_cvt_pk_bf16_f32 v1, v10, v11
	v_cvt_pk_bf16_f32 v3, v6, v7
	v_lshl_add_u64 v[4:5], v[4:5], 0, v[106:107]
	global_store_dwordx4 v[4:5], v[0:3], off
	s_cbranch_vccnz .LBB0_872
	s_andn2_b64 vcc, exec, s[12:13]
	s_cbranch_vccnz .LBB0_871
	s_barrier
	s_branch .LBB0_871

; #define PG8_STAGE(bufoff, gbase, voff) do { _Pragma("unroll") for (int _i = 0; _i < 2; ++_i) \
;         __builtin_amdgcn_global_load_lds((const unsigned*)((const char*)(gbase) + (voff)[_i]), (LAS unsigned*)(lds + (bufoff) + ldsw + _i * 8192), 16, 0, 0); } while (0)
; #define PG8_WAIT_V(n) asm volatile("s_waitcnt vmcnt(" #n ")" ::: "memory")
; #define PG8_BAR __builtin_amdgcn_s_barrier()
; template <class Epi>
; __device__ __forceinline__ void gemm_phase(LAS unsigned char* lds, const Gemm g, const StaticOrder& S, const Epi& E) {
;     ...
;     const int tid = tid_, wid = __builtin_amdgcn_readfirstlane(tid >> 6), lane = tid & 63, wr = wid >> 2, wc = wid & 3, fr = lane & 15, fq = lane >> 4;
;     const int K = g.K, nt = K / BK, lda = g.lda;
;     unsigned voffA[2], voffB[2];
; #pragma unroll
;     for (int i = 0; i < 2; ++i) { int R, C; stage_rc(tid * 16 + i * 8192, R, C); const int Rb = (R & ~31) + perm32(R & 31);
;         voffA[i] = (unsigned)(R * lda + C) * 2u; voffB[i] = (unsigned)(Rb * K + C) * 2u; }
;     const unsigned kstep = (unsigned)(BK * 2);
;     const unsigned hstepA = (unsigned)(HALF * lda * 2), hstepB = (unsigned)(HALF * K * 2);
;     const size_t tstepA = 2 * (size_t)hstepA, tstepB = 2 * (size_t)hstepB;
;     const unsigned ldsw = (unsigned)wid * 1024u;
;     const int aoff = lds_byte(wr * 64 + fr, fq * 8), boff = lds_byte(wc * 32 + fr, fq * 8);
;     ...
;     Unit cur, nxt; int ui = 0;
;     if (!S.next(0, cur)) return;
;     f32x4 acc[2][2][4][2];
; #pragma unroll
;     for (int a = 0; a < 2; ++a)
; #pragma unroll
;         for (int b = 0; b < 2; ++b)
; #pragma unroll
;             for (int m = 0; m < 4; ++m)
; #pragma unroll
;                 for (int n = 0; n < 2; ++n) acc[a][b][m][n] = (f32x4){0.f, 0.f, 0.f, 0.f};
;     bf16x8 At[4][2], B0[2][2], B1[2][2];
;     const char* cA = (const char*)g.A + (size_t)cur.pm * tstepA; const char* cB = (const char*)g.Bt + (size_t)cur.pn * tstepB;
;     PG8_STAGE(PG8_SB(0, 0), cB, voffB); PG8_STAGE(PG8_SB(0, 1), cB + hstepB, voffB); PG8_STAGE(PG8_SA(0, 0), cA, voffA); PG8_STAGE(PG8_SA(0, 1), cA + hstepA, voffA);
;     if (wr == 1) PG8_BAR;
;     PG8_WAIT_V(2); PG8_BAR;
;     PG8_STAGE(PG8_SB(1, 0), cB + kstep, voffB); PG8_STAGE(PG8_SA(1, 0), cA + kstep, voffA); PG8_STAGE(PG8_SB(1, 1), cB + hstepB + kstep, voffB);
;     PG8_WAIT_V(6); PG8_BAR;
.LBB0_1406:
	s_or_b64 exec, exec, s[40:41]
	s_mov_b64 s[16:17], s[42:43]
	v_mov_b32_e32 v9, v154
	s_waitcnt lgkmcnt(0)
	s_barrier
	s_cselect_b32 s92, 1, 0
	s_cmp_lt_u32 s14, 128
	s_cbranch_scc1 .Lstg_0
	s_sleep 127
	s_sleep 127
	s_sleep 127
	s_sleep 127
	s_sleep 127
.Lstg_0:
	s_cmp_lg_u32 s92, 0
	s_and_b64 vcc, exec, s[2:3]
	v_readfirstlane_b32 s3, v9
	s_cbranch_vccnz .LBB0_1422
	v_lshlrev_b32_e32 v0, 4, v9
	v_add_u32_e32 v1, 0x2000, v0
	v_ashrrev_i32_e32 v2, 31, v1
	v_lshrrev_b32_e32 v2, 22, v2
	v_add_u32_e32 v2, v1, v2
	v_ashrrev_i32_e32 v8, 10, v2
	v_mul_i32_i24_e32 v2, 0x400, v8
	v_sub_u32_e32 v1, v1, v2
	v_lshrrev_b32_e32 v2, 4, v1
	v_bitop3_b32 v1, v2, v1, 32 bitop3:0x6c
	v_ashrrev_i32_e32 v2, 31, v1
	v_lshrrev_b32_e32 v2, 26, v2
	v_add_u32_e32 v2, v1, v2
	v_lshlrev_b32_e32 v3, 3, v8
	v_ashrrev_i32_e32 v10, 6, v2
	v_and_b32_e32 v3, -16, v3
	v_add_u32_e32 v3, v10, v3
	v_and_b32_e32 v4, 3, v10
	s_mov_b32 s2, 0x1fffe0
	v_lshrrev_b32_e32 v5, 2, v3
	v_lshlrev_b32_e32 v6, 1, v3
	v_and_b32_e32 v2, 0xc0, v2
	v_and_or_b32 v4, v3, s2, v4
	v_and_b32_e32 v5, 4, v5
	v_and_b32_e32 v6, 24, v6
	v_sub_u32_e32 v1, v1, v2
	v_mov_b32_e32 v2, 1
	v_or3_b32 v4, v4, v5, v6
	v_lshlrev_b32_e32 v5, 5, v8
	v_ashrrev_i16_sdwa v1, v2, sext(v1) dst_sel:DWORD dst_unused:UNUSED_PAD src0_sel:DWORD src1_sel:BYTE_0
	v_and_b32_e32 v5, 32, v5
	v_bfe_i32 v11, v1, 0, 16
	v_add_lshl_u32 v1, v5, v11, 1
	v_lshl_add_u32 v128, v4, 11, v1
	v_lshl_add_u32 v130, v3, 11, v1
	v_bfe_i32 v1, v9, 27, 1
	v_lshrrev_b32_e32 v1, 22, v1
	v_add_u32_e32 v1, v0, v1
	v_and_b32_e32 v1, 0xfffffc00, v1
	v_sub_u32_e32 v0, v0, v1
	v_lshrrev_b32_e32 v1, 4, v0
	v_ashrrev_i32_e32 v3, 31, v9
	v_bitop3_b32 v0, v1, v0, 32 bitop3:0x6c
	v_lshrrev_b32_e32 v3, 26, v3
	v_ashrrev_i32_e32 v1, 31, v0
	v_add_u32_e32 v3, v9, v3
	s_add_u32 s33, s16, 0x5400000
	v_lshrrev_b32_e32 v1, 26, v1
	v_ashrrev_i32_e32 v13, 6, v3
	s_addc_u32 s34, s17, 0
	v_add_u32_e32 v1, v0, v1
	v_lshlrev_b32_e32 v3, 3, v13
	s_add_u32 s35, s16, 0x4380000
	v_ashrrev_i32_e32 v12, 6, v1
	v_and_b32_e32 v3, -16, v3
	s_addc_u32 s36, s17, 0
	v_add_u32_e32 v3, v12, v3
	v_and_b32_e32 v4, 3, v12
	s_ashr_i32 s38, s14, 31
	v_and_or_b32 v4, v3, s2, v4
	s_lshr_b32 s2, s38, 29
	s_add_i32 s2, s14, s2
	s_ashr_i32 s10, s3, 6
	s_ashr_i32 s4, s2, 3
	s_and_b32 s2, s2, -8
	s_ashr_i32 s12, s3, 8
	s_lshl_b32 s37, s10, 10
	s_sub_i32 s2, s14, s2
	s_cmp_lt_i32 s2, 0
	s_movk_i32 s39, 0x211
	s_cselect_b32 s5, s39, 0x210
	s_mul_i32 s2, s2, s5
	s_add_i32 s2, s2, s4
	s_mul_hi_i32 s4, s2, 0x2e8ba2e9
	s_lshr_b32 s5, s4, 31
	s_ashr_i32 s4, s4, 5
	s_add_i32 s4, s4, s5
	s_lshl_b32 s5, s4, 3
	s_mulk_i32 s4, 0xb0
	s_sub_i32 s4, s2, s4
	s_sext_i32_i16 s2, s4
	s_bfe_u32 s2, s2, 0x3001c
	s_add_i32 s8, s4, s2
	s_sext_i32_i16 s2, s8
	s_and_b32 s8, s8, 0xfff8
	s_sub_i32 s4, s4, s8
	s_sext_i32_i16 s4, s4
	v_lshrrev_b32_e32 v5, 2, v3
	v_lshlrev_b32_e32 v6, 1, v3
	v_and_b32_e32 v1, 0xc0, v1
	s_lshr_b32 s2, s2, 3
	s_add_i32 s24, s5, s4
	v_and_b32_e32 v5, 4, v5
	v_and_b32_e32 v6, 24, v6
	v_sub_u32_e32 v0, v0, v1
	s_ashr_i32 s25, s24, 31
	s_bfe_i64 s[8:9], s[2:3], 0x100000
	v_or3_b32 v4, v4, v5, v6
	v_lshlrev_b32_e32 v5, 5, v13
	v_ashrrev_i16_sdwa v0, v2, sext(v0) dst_sel:DWORD dst_unused:UNUSED_PAD src0_sel:DWORD src1_sel:BYTE_0
	s_lshl_b64 s[4:5], s[24:25], 19
	s_lshl_b64 s[8:9], s[8:9], 19
	v_and_b32_e32 v5, 32, v5
	v_bfe_i32 v14, v0, 0, 16
	s_add_u32 s26, s35, s8
	v_add_lshl_u32 v0, v5, v14, 1
	s_addc_u32 s27, s36, s9
	s_add_i32 s25, s37, 0
	v_lshl_add_u32 v132, v4, 11, v0
	s_add_i32 m0, s25, 0x10000
	v_lshl_add_u32 v134, v3, 11, v0
	global_load_lds_dwordx4 v132, s[26:27]
	s_add_i32 m0, s25, 0x12000
	s_add_u32 s8, s26, 0x40000
	global_load_lds_dwordx4 v128, s[26:27]
	s_addc_u32 s9, s27, 0
	s_add_i32 m0, s25, 0x14000
	v_mov_b32_e32 v133, 0
	global_load_lds_dwordx4 v132, s[8:9]
	s_add_i32 m0, s25, 0x16000
	s_add_u32 s28, s33, s4
	s_addc_u32 s29, s34, s5
	s_add_i32 s40, s25, 0x2000
	global_load_lds_dwordx4 v128, s[8:9]
	s_mov_b32 m0, s25
	s_add_u32 s4, s28, 0x40000
	global_load_lds_dwordx4 v134, s[28:29]
	s_mov_b32 m0, s40
	s_addc_u32 s5, s29, 0
	s_add_i32 s41, s25, 0x4000
	global_load_lds_dwordx4 v130, s[28:29]
	s_mov_b32 m0, s41
	s_add_i32 s44, s25, 0x6000
	global_load_lds_dwordx4 v134, s[4:5]
	s_mov_b32 m0, s44
	v_mov_b32_e32 v129, v133
	global_load_lds_dwordx4 v130, s[4:5]
	v_mov_b32_e32 v135, v133
	v_mov_b32_e32 v131, v133
	s_cmp_eq_u32 s12, 1
	s_mov_b32 s45, 0
	v_lshl_add_u64 v[6:7], s[26:27], 0, v[132:133]
	v_lshl_add_u64 v[4:5], s[26:27], 0, v[128:129]
	v_lshl_add_u64 v[0:1], s[28:29], 0, v[134:135]
	s_cselect_b64 s[4:5], -1, 0
	s_cmp_lg_u32 s12, 1
	v_lshl_add_u64 v[2:3], s[28:29], 0, v[130:131]
	s_cbranch_scc1 .LBB0_1409
	s_barrier
